# v9 + write-through (sc0 sc1) output stores in GEMM store epilogues and attention O stores: less dirty L2 to write back at each grid barrier
# speedup vs baseline: 1.0076x; 1.0076x over previous
; #define LAS __attribute__((address_space(3)))
; #define GASA __attribute__((address_space(1)))
; DI unsigned pk2(float lo, float hi) { f32x2 v = {lo, hi}; bf16x2_t b = __builtin_convertvector(v, bf16x2_t); return __builtin_bit_cast(unsigned, b); }
; template <int DQK, int DV, bool BAND>
; DI void attn_unit(const AttnArgs& a, LAS unsigned char* lds, int tid) {
;     ...
;     asm volatile("s_waitcnt lgkmcnt(0)\n\ts_barrier" ::: "memory");
;     __builtin_amdgcn_s_setprio(0);
;     { if (a.lse != nullptr) {
;           if (hi == 0) scr[r32] = m_run;
; #pragma unroll
;           for (int g = 0; g < 4; ++g) { const f32x4 mr = *(const LAS f32x4*)(scr + 8 * g + 4 * hi);
; #pragma unroll
;               for (int e = 0; e < 4; ++e) if (r32 == 0) ((GASA float*)a.lse)[(long)(wid * 32 + 8 * g + 4 * hi + e) * a.lses] = mr[e] + __builtin_amdgcn_logf(lacc[4 * g + e]); } }
;       LAS bf16_t* stg = (LAS bf16_t*)(lds + wid * 8192);
; #pragma unroll
;       for (int g = 0; g < 4; ++g) {
; #pragma unroll
;           for (int e = 0; e < 4; ++e) { const int orow = 8 * g + 4 * hi + e; const float rr = __builtin_amdgcn_rcpf(lacc[4 * g + e]);
; #pragma unroll
;               for (int d = 0; d < NDB; ++d) stg[orow * DV + d * 32 + r32] = (bf16_t)(pk2(o[d][4 * g + e] * rr, 0.f) & 0xffffu); } }
;       constexpr int CPR = DV / 8, RPI = 64 / CPR;
; #pragma unroll
;       for (int i = 0; i < 32 / RPI; ++i) { const int row = i * RPI + lane / CPR, ch = lane % CPR;
;           const u32x4 v = *(const LAS u32x4*)(stg + row * DV + ch * 8); *(GASA u32x4*)((GASA bf16_t*)a.o + (long)(wid * 32 + row) * a.os + ch * 8) = v; }
.LBB0_124:
	s_lshl_b64 s[26:27], s[42:43], 1
	s_add_u32 s26, s72, s26
	s_waitcnt lgkmcnt(0)
	s_barrier
	s_addc_u32 s27, s73, s27
	s_add_u32 s40, s26, s24
	s_addc_u32 s41, s27, 0
	s_setprio 0
	s_nop 4
	v_rcp_f32_e32 v64, v64
	s_lshl_b32 s19, s19, 13
	s_add_i32 s19, s19, 0
	v_lshlrev_b32_e32 v80, 1, v182
	v_mul_f32_e32 v16, v16, v64
	v_add3_u32 v80, s19, v80, v184
	v_cvt_pk_bf16_f32 v16, v16, s0
	ds_write_b16 v80, v16 offset:128
	v_rcp_f32_e32 v16, v65
	v_mul_f32_e32 v0, v0, v64
	v_cvt_pk_bf16_f32 v0, v0, s0
	ds_write_b16 v80, v0 offset:192
	v_mul_f32_e32 v0, v49, v16
	v_cvt_pk_bf16_f32 v0, v0, s0
	ds_write_b16 v80, v0 offset:256
	v_mul_f32_e32 v0, v33, v16
	v_cvt_pk_bf16_f32 v0, v0, s0
	ds_write_b16 v80, v0 offset:320
	v_mul_f32_e32 v0, v17, v16
	v_cvt_pk_bf16_f32 v0, v0, s0
	ds_write_b16 v80, v0 offset:384
	v_rcp_f32_e32 v0, v66
	v_mul_f32_e32 v1, v1, v16
	v_cvt_pk_bf16_f32 v1, v1, s0
	ds_write_b16 v80, v1 offset:448
	v_mul_f32_e32 v1, v50, v0
	v_cvt_pk_bf16_f32 v1, v1, s0
	ds_write_b16 v80, v1 offset:512
	v_mul_f32_e32 v1, v34, v0
	v_cvt_pk_bf16_f32 v1, v1, s0
	ds_write_b16 v80, v1 offset:576
	v_mul_f32_e32 v1, v18, v0
	v_cvt_pk_bf16_f32 v1, v1, s0
	ds_write_b16 v80, v1 offset:640
	v_rcp_f32_e32 v1, v67
	v_mul_f32_e32 v0, v2, v0
	v_cvt_pk_bf16_f32 v0, v0, s0
	ds_write_b16 v80, v0 offset:704
	v_mul_f32_e32 v0, v51, v1
	v_cvt_pk_bf16_f32 v0, v0, s0
	ds_write_b16 v80, v0 offset:768
	v_mul_f32_e32 v0, v35, v1
	v_cvt_pk_bf16_f32 v0, v0, s0
	ds_write_b16 v80, v0 offset:832
	v_mul_f32_e32 v0, v19, v1
	v_cvt_pk_bf16_f32 v0, v0, s0
	ds_write_b16 v80, v0 offset:896
	v_rcp_f32_e32 v0, v68
	v_mul_f32_e32 v1, v3, v1
	v_cvt_pk_bf16_f32 v1, v1, s0
	ds_write_b16 v80, v1 offset:960
	v_mul_f32_e32 v1, v52, v0
	v_cvt_pk_bf16_f32 v1, v1, s0
	ds_write_b16 v80, v1 offset:2048
	v_mul_f32_e32 v1, v36, v0
	v_cvt_pk_bf16_f32 v1, v1, s0
	ds_write_b16 v80, v1 offset:2112
	v_mul_f32_e32 v1, v20, v0
	v_cvt_pk_bf16_f32 v1, v1, s0
	ds_write_b16 v80, v1 offset:2176
	v_rcp_f32_e32 v1, v69
	v_mul_f32_e32 v0, v4, v0
	v_cvt_pk_bf16_f32 v0, v0, s0
	ds_write_b16 v80, v0 offset:2240
	v_mul_f32_e32 v0, v53, v1
	v_cvt_pk_bf16_f32 v0, v0, s0
	ds_write_b16 v80, v0 offset:2304
	v_mul_f32_e32 v0, v37, v1
	v_cvt_pk_bf16_f32 v0, v0, s0
	ds_write_b16 v80, v0 offset:2368
	v_mul_f32_e32 v0, v21, v1
	v_cvt_pk_bf16_f32 v0, v0, s0
	ds_write_b16 v80, v0 offset:2432
	v_rcp_f32_e32 v0, v70
	v_mul_f32_e32 v1, v5, v1
	v_cvt_pk_bf16_f32 v1, v1, s0
	ds_write_b16 v80, v1 offset:2496
	v_mul_f32_e32 v1, v54, v0
	v_cvt_pk_bf16_f32 v1, v1, s0
	ds_write_b16 v80, v1 offset:2560
	v_mul_f32_e32 v1, v38, v0
	v_cvt_pk_bf16_f32 v1, v1, s0
	ds_write_b16 v80, v1 offset:2624
	v_mul_f32_e32 v1, v22, v0
	v_cvt_pk_bf16_f32 v1, v1, s0
	ds_write_b16 v80, v1 offset:2688
	v_rcp_f32_e32 v1, v71
	v_mul_f32_e32 v0, v6, v0
	v_cvt_pk_bf16_f32 v0, v0, s0
	ds_write_b16 v80, v0 offset:2752
	v_mul_f32_e32 v0, v55, v1
	v_cvt_pk_bf16_f32 v0, v0, s0
	ds_write_b16 v80, v0 offset:2816
	v_mul_f32_e32 v0, v39, v1
	v_cvt_pk_bf16_f32 v0, v0, s0
	ds_write_b16 v80, v0 offset:2880
	v_mul_f32_e32 v0, v23, v1
	v_cvt_pk_bf16_f32 v0, v0, s0
	ds_write_b16 v80, v0 offset:2944
	v_rcp_f32_e32 v0, v72
	v_mul_f32_e32 v1, v7, v1
	v_cvt_pk_bf16_f32 v1, v1, s0
	ds_write_b16 v80, v1 offset:3008
	v_mul_f32_e32 v1, v56, v0
	v_cvt_pk_bf16_f32 v1, v1, s0
	ds_write_b16 v80, v1 offset:4096
	v_mul_f32_e32 v1, v40, v0
	v_cvt_pk_bf16_f32 v1, v1, s0
	ds_write_b16 v80, v1 offset:4160
	v_mul_f32_e32 v1, v24, v0
	v_cvt_pk_bf16_f32 v1, v1, s0
	ds_write_b16 v80, v1 offset:4224
	v_rcp_f32_e32 v1, v73
	v_mul_f32_e32 v0, v8, v0
	v_cvt_pk_bf16_f32 v0, v0, s0
	ds_write_b16 v80, v0 offset:4288
	v_mul_f32_e32 v0, v57, v1
	v_cvt_pk_bf16_f32 v0, v0, s0
	ds_write_b16 v80, v0 offset:4352
	v_mul_f32_e32 v0, v41, v1
	v_cvt_pk_bf16_f32 v0, v0, s0
	ds_write_b16 v80, v0 offset:4416
	v_mul_f32_e32 v0, v25, v1
	v_cvt_pk_bf16_f32 v0, v0, s0
	ds_write_b16 v80, v0 offset:4480
	v_rcp_f32_e32 v0, v74
	v_mul_f32_e32 v1, v9, v1
	v_cvt_pk_bf16_f32 v1, v1, s0
	ds_write_b16 v80, v1 offset:4544
	v_mul_f32_e32 v1, v58, v0
	v_cvt_pk_bf16_f32 v1, v1, s0
	ds_write_b16 v80, v1 offset:4608
	v_mul_f32_e32 v1, v42, v0
	v_cvt_pk_bf16_f32 v1, v1, s0
	ds_write_b16 v80, v1 offset:4672
	v_mul_f32_e32 v1, v26, v0
	v_cvt_pk_bf16_f32 v1, v1, s0
	ds_write_b16 v80, v1 offset:4736
	v_rcp_f32_e32 v1, v75
	v_mul_f32_e32 v0, v10, v0
	v_cvt_pk_bf16_f32 v0, v0, s0
	ds_write_b16 v80, v0 offset:4800
	v_mul_f32_e32 v0, v59, v1
	v_cvt_pk_bf16_f32 v0, v0, s0
	ds_write_b16 v80, v0 offset:4864
	v_mul_f32_e32 v0, v43, v1
	v_cvt_pk_bf16_f32 v0, v0, s0
	ds_write_b16 v80, v0 offset:4928
	v_mul_f32_e32 v0, v27, v1
	v_cvt_pk_bf16_f32 v0, v0, s0
	ds_write_b16 v80, v0 offset:4992
	v_rcp_f32_e32 v0, v76
	v_mul_f32_e32 v1, v11, v1
	v_cvt_pk_bf16_f32 v1, v1, s0
	ds_write_b16 v80, v1 offset:5056
	v_mul_f32_e32 v1, v60, v0
	v_cvt_pk_bf16_f32 v1, v1, s0
	ds_write_b16 v80, v1 offset:6144
	v_mul_f32_e32 v1, v44, v0
	v_cvt_pk_bf16_f32 v1, v1, s0
	ds_write_b16 v80, v1 offset:6208
	v_mul_f32_e32 v1, v28, v0
	v_cvt_pk_bf16_f32 v1, v1, s0
	ds_write_b16 v80, v1 offset:6272
	v_rcp_f32_e32 v1, v77
	v_mul_f32_e32 v0, v12, v0
	v_cvt_pk_bf16_f32 v0, v0, s0
	ds_write_b16 v80, v0 offset:6336
	v_mul_f32_e32 v0, v61, v1
	v_cvt_pk_bf16_f32 v0, v0, s0
	ds_write_b16 v80, v0 offset:6400
	v_mul_f32_e32 v0, v45, v1
	v_cvt_pk_bf16_f32 v0, v0, s0
	ds_write_b16 v80, v0 offset:6464
	v_mul_f32_e32 v0, v29, v1
	v_cvt_pk_bf16_f32 v0, v0, s0
	ds_write_b16 v80, v0 offset:6528
	v_rcp_f32_e32 v0, v78
	v_mul_f32_e32 v1, v13, v1
	v_cvt_pk_bf16_f32 v1, v1, s0
	ds_write_b16 v80, v1 offset:6592
	v_mul_f32_e32 v1, v62, v0
	v_cvt_pk_bf16_f32 v1, v1, s0
	ds_write_b16 v80, v1 offset:6656
	v_mul_f32_e32 v1, v46, v0
	v_cvt_pk_bf16_f32 v1, v1, s0
	ds_write_b16 v80, v1 offset:6720
	v_mul_f32_e32 v1, v30, v0
	v_cvt_pk_bf16_f32 v1, v1, s0
	ds_write_b16 v80, v1 offset:6784
	v_rcp_f32_e32 v1, v79
	v_mul_f32_e32 v0, v14, v0
	v_cvt_pk_bf16_f32 v0, v0, s0
	ds_write_b16 v80, v0 offset:6848
	v_mul_f32_e32 v0, v63, v1
	v_cvt_pk_bf16_f32 v0, v0, s0
	ds_write_b16 v80, v0 offset:6912
	v_mul_f32_e32 v0, v47, v1
	v_cvt_pk_bf16_f32 v0, v0, s0
	ds_write_b16 v80, v0 offset:6976
	v_mul_f32_e32 v0, v31, v1
	v_cvt_pk_bf16_f32 v0, v0, s0
	v_mul_f32_e32 v48, v48, v64
	v_mul_f32_e32 v32, v32, v64
	ds_write_b16 v80, v0 offset:7040
	v_mul_f32_e32 v0, v15, v1
	v_cvt_pk_bf16_f32 v48, v48, s0
	v_cvt_pk_bf16_f32 v32, v32, s0
	v_cvt_pk_bf16_f32 v0, v0, s0
	v_add_u32_e32 v10, s19, v170
	ds_write_b16 v80, v48
	ds_write_b16 v80, v32 offset:64
	ds_write_b16 v80, v0 offset:7104
	v_add_u32_e32 v0, v10, v189
	ds_read_b128 v[0:3], v0
	v_or_b32_e32 v4, s18, v188
	v_ashrrev_i32_e32 v5, 31, v4
	v_lshlrev_b64 v[4:5], 10, v[4:5]
	v_lshl_add_u64 v[4:5], s[40:41], 0, v[4:5]
	v_mov_b32_e32 v171, v195
	v_lshl_add_u64 v[8:9], v[4:5], 0, v[170:171]
	v_add_u32_e32 v4, v10, v191
	ds_read_b128 v[4:7], v4
	s_waitcnt lgkmcnt(1)
; #define LAS __attribute__((address_space(3)))
; #define GASA __attribute__((address_space(1)))
; template <int DQK, int DV, bool BAND>
; DI void attn_unit(const AttnArgs& a, LAS unsigned char* lds, int tid) {
;     ...
;       constexpr int CPR = DV / 8, RPI = 64 / CPR;
; #pragma unroll
;       for (int i = 0; i < 32 / RPI; ++i) { const int row = i * RPI + lane / CPR, ch = lane % CPR;
;           const u32x4 v = *(const LAS u32x4*)(stg + row * DV + ch * 8); *(GASA u32x4*)((GASA bf16_t*)a.o + (long)(wid * 32 + row) * a.os + ch * 8) = v; }
	global_store_dwordx4 v[8:9], v[0:3], off sc0 sc1
	s_add_i32 s17, s17, s58
	s_nop 0
	v_or_b32_e32 v0, s18, v190
	v_ashrrev_i32_e32 v1, 31, v0
	v_lshlrev_b64 v[0:1], 10, v[0:1]
	v_lshl_add_u64 v[0:1], s[40:41], 0, v[0:1]
	v_lshl_add_u64 v[0:1], v[0:1], 0, v[170:171]
	s_waitcnt lgkmcnt(0)
	global_store_dwordx4 v[0:1], v[4:7], off sc0 sc1
	v_add_u32_e32 v0, v10, v198
	ds_read_b128 v[0:3], v0
	v_or_b32_e32 v4, s18, v196
	v_ashrrev_i32_e32 v5, 31, v4
	v_lshlrev_b64 v[4:5], 10, v[4:5]
	v_lshl_add_u64 v[4:5], s[40:41], 0, v[4:5]
	v_lshl_add_u64 v[8:9], v[4:5], 0, v[170:171]
	v_add_u32_e32 v4, v10, v200
	ds_read_b128 v[4:7], v4
	s_waitcnt lgkmcnt(1)
	global_store_dwordx4 v[8:9], v[0:3], off sc0 sc1
	s_nop 1
	v_or_b32_e32 v0, s18, v199
	v_ashrrev_i32_e32 v1, 31, v0
	v_lshlrev_b64 v[0:1], 10, v[0:1]
	v_lshl_add_u64 v[0:1], s[40:41], 0, v[0:1]
	v_lshl_add_u64 v[0:1], v[0:1], 0, v[170:171]
	s_waitcnt lgkmcnt(0)
	global_store_dwordx4 v[0:1], v[4:7], off sc0 sc1
	v_add_u32_e32 v0, v10, v203
	ds_read_b128 v[0:3], v0
	v_or_b32_e32 v4, s18, v201
	v_ashrrev_i32_e32 v5, 31, v4
	v_lshlrev_b64 v[4:5], 10, v[4:5]
	v_lshl_add_u64 v[4:5], s[40:41], 0, v[4:5]
	v_lshl_add_u64 v[8:9], v[4:5], 0, v[170:171]
	v_add_u32_e32 v4, v10, v205
	ds_read_b128 v[4:7], v4
	s_waitcnt lgkmcnt(1)
	global_store_dwordx4 v[8:9], v[0:3], off sc0 sc1
	s_nop 1
	v_or_b32_e32 v0, s18, v204
	v_ashrrev_i32_e32 v1, 31, v0
	v_lshlrev_b64 v[0:1], 10, v[0:1]
	v_lshl_add_u64 v[0:1], s[40:41], 0, v[0:1]
	v_lshl_add_u64 v[0:1], v[0:1], 0, v[170:171]
	s_waitcnt lgkmcnt(0)
	global_store_dwordx4 v[0:1], v[4:7], off sc0 sc1
	v_add_u32_e32 v0, v10, v207
	ds_read_b128 v[0:3], v0
	v_or_b32_e32 v4, s18, v206
	v_ashrrev_i32_e32 v5, 31, v4
	v_lshlrev_b64 v[4:5], 10, v[4:5]
	v_lshl_add_u64 v[4:5], s[40:41], 0, v[4:5]
	v_lshl_add_u64 v[8:9], v[4:5], 0, v[170:171]
	v_add_u32_e32 v4, v10, v209
	ds_read_b128 v[4:7], v4
	s_waitcnt lgkmcnt(1)
	global_store_dwordx4 v[8:9], v[0:3], off sc0 sc1
	s_nop 1
	v_or_b32_e32 v0, s18, v208
	v_ashrrev_i32_e32 v1, 31, v0
	v_lshlrev_b64 v[0:1], 10, v[0:1]
	v_readlane_b32 s18, v253, 33
	v_lshl_add_u64 v[0:1], s[40:41], 0, v[0:1]
	s_add_i32 s16, s16, s18
	v_lshl_add_u64 v[0:1], v[0:1], 0, v[170:171]
	s_cmpk_gt_i32 s17, 0xff
	s_waitcnt lgkmcnt(0)
	global_store_dwordx4 v[0:1], v[4:7], off sc0 sc1
	s_barrier
	s_cbranch_scc1 .LBB0_163

; #define LAS __attribute__((address_space(3)))
; #define GASA __attribute__((address_space(1)))
; DI unsigned pk2(float lo, float hi) { f32x2 v = {lo, hi}; bf16x2_t b = __builtin_convertvector(v, bf16x2_t); return __builtin_bit_cast(unsigned, b); }
; template <int DQK, int DV, bool BAND>
; DI void attn_unit(const AttnArgs& a, LAS unsigned char* lds, int tid) {
;     ...
;     asm volatile("s_waitcnt lgkmcnt(0)\n\ts_barrier" ::: "memory");
;     __builtin_amdgcn_s_setprio(0);
;     { if (a.lse != nullptr) {
;           if (hi == 0) scr[r32] = m_run;
; #pragma unroll
;           for (int g = 0; g < 4; ++g) { const f32x4 mr = *(const LAS f32x4*)(scr + 8 * g + 4 * hi);
; #pragma unroll
;               for (int e = 0; e < 4; ++e) if (r32 == 0) ((GASA float*)a.lse)[(long)(wid * 32 + 8 * g + 4 * hi + e) * a.lses] = mr[e] + __builtin_amdgcn_logf(lacc[4 * g + e]); } }
;       LAS bf16_t* stg = (LAS bf16_t*)(lds + wid * 8192);
; #pragma unroll
;       for (int g = 0; g < 4; ++g) {
; #pragma unroll
;           for (int e = 0; e < 4; ++e) { const int orow = 8 * g + 4 * hi + e; const float rr = __builtin_amdgcn_rcpf(lacc[4 * g + e]);
; #pragma unroll
;               for (int d = 0; d < NDB; ++d) stg[orow * DV + d * 32 + r32] = (bf16_t)(pk2(o[d][4 * g + e] * rr, 0.f) & 0xffffu); } }
;       constexpr int CPR = DV / 8, RPI = 64 / CPR;
; #pragma unroll
;       for (int i = 0; i < 32 / RPI; ++i) { const int row = i * RPI + lane / CPR, ch = lane % CPR;
;           const u32x4 v = *(const LAS u32x4*)(stg + row * DV + ch * 8); *(GASA u32x4*)((GASA bf16_t*)a.o + (long)(wid * 32 + row) * a.os + ch * 8) = v; }
.LBB0_167:
	s_lshl_b64 s[40:41], s[42:43], 11
	s_add_u32 s24, s72, s40
	s_addc_u32 s42, s73, s41
	s_lshl_b32 s40, s34, 6
	s_ashr_i32 s41, s40, 31
	s_waitcnt lgkmcnt(0)
	s_barrier
	s_lshl_b64 s[40:41], s[40:41], 1
	s_add_u32 s40, s24, s40
	s_addc_u32 s41, s42, s41
	s_setprio 0
	s_nop 1
	v_add_f32_e32 v46, v46, v47
	s_nop 0
	v_mov_b32_e32 v47, v46
	s_nop 1
	v_permlane32_swap_b32_e32 v46, v47
	s_nop 1
	v_add_f32_e32 v46, v46, v47
	ds_write_b32 v171, v46
	s_waitcnt lgkmcnt(0)
	ds_read_b128 v[32:35], v173
	ds_read_b128 v[36:39], v173 offset:32
	ds_read_b128 v[40:43], v173 offset:64
	ds_read_b128 v[44:47], v173 offset:96
	s_waitcnt lgkmcnt(0)
	v_rcp_f32_e32 v32, v32
	s_lshl_b32 s24, s35, 13
	s_add_i32 s24, s24, 0
	v_lshlrev_b32_e32 v48, 1, v157
	v_mul_f32_e32 v0, v0, v32
	v_add3_u32 v48, s24, v48, v186
	v_cvt_pk_bf16_f32 v0, v0, s0
	ds_write_b16 v48, v0
	v_rcp_f32_e32 v0, v33
	v_mul_f32_e32 v16, v16, v32
	v_cvt_pk_bf16_f32 v16, v16, s0
	ds_write_b16 v48, v16 offset:64
	v_mul_f32_e32 v1, v1, v0
	v_cvt_pk_bf16_f32 v1, v1, s0
	ds_write_b16 v48, v1 offset:128
	v_rcp_f32_e32 v1, v34
	v_mul_f32_e32 v0, v17, v0
	v_cvt_pk_bf16_f32 v0, v0, s0
	ds_write_b16 v48, v0 offset:192
	v_mul_f32_e32 v0, v2, v1
	v_cvt_pk_bf16_f32 v0, v0, s0
	ds_write_b16 v48, v0 offset:256
	v_rcp_f32_e32 v0, v35
	v_mul_f32_e32 v1, v18, v1
	v_cvt_pk_bf16_f32 v1, v1, s0
	ds_write_b16 v48, v1 offset:320
	v_mul_f32_e32 v1, v3, v0
	v_cvt_pk_bf16_f32 v1, v1, s0
	ds_write_b16 v48, v1 offset:384
	v_rcp_f32_e32 v1, v36
	v_mul_f32_e32 v0, v19, v0
	v_cvt_pk_bf16_f32 v0, v0, s0
	ds_write_b16 v48, v0 offset:448
	v_mul_f32_e32 v0, v4, v1
	v_cvt_pk_bf16_f32 v0, v0, s0
	ds_write_b16 v48, v0 offset:1024
	v_rcp_f32_e32 v0, v37
	v_mul_f32_e32 v1, v20, v1
	v_cvt_pk_bf16_f32 v1, v1, s0
	ds_write_b16 v48, v1 offset:1088
	v_mul_f32_e32 v1, v5, v0
	v_cvt_pk_bf16_f32 v1, v1, s0
	ds_write_b16 v48, v1 offset:1152
	v_rcp_f32_e32 v1, v38
	v_mul_f32_e32 v0, v21, v0
	v_cvt_pk_bf16_f32 v0, v0, s0
	ds_write_b16 v48, v0 offset:1216
	v_mul_f32_e32 v0, v6, v1
	v_cvt_pk_bf16_f32 v0, v0, s0
	ds_write_b16 v48, v0 offset:1280
	v_rcp_f32_e32 v0, v39
	v_mul_f32_e32 v1, v22, v1
	v_cvt_pk_bf16_f32 v1, v1, s0
	ds_write_b16 v48, v1 offset:1344
	v_mul_f32_e32 v1, v7, v0
	v_cvt_pk_bf16_f32 v1, v1, s0
	ds_write_b16 v48, v1 offset:1408
	v_rcp_f32_e32 v1, v40
	v_mul_f32_e32 v0, v23, v0
	v_cvt_pk_bf16_f32 v0, v0, s0
	ds_write_b16 v48, v0 offset:1472
	v_mul_f32_e32 v0, v8, v1
	v_cvt_pk_bf16_f32 v0, v0, s0
	ds_write_b16 v48, v0 offset:2048
	v_rcp_f32_e32 v0, v41
	v_mul_f32_e32 v1, v24, v1
	v_cvt_pk_bf16_f32 v1, v1, s0
	ds_write_b16 v48, v1 offset:2112
	v_mul_f32_e32 v1, v9, v0
	v_cvt_pk_bf16_f32 v1, v1, s0
	ds_write_b16 v48, v1 offset:2176
	v_rcp_f32_e32 v1, v42
	v_mul_f32_e32 v0, v25, v0
	v_cvt_pk_bf16_f32 v0, v0, s0
	ds_write_b16 v48, v0 offset:2240
	v_mul_f32_e32 v0, v10, v1
	v_cvt_pk_bf16_f32 v0, v0, s0
	ds_write_b16 v48, v0 offset:2304
	v_rcp_f32_e32 v0, v43
	v_mul_f32_e32 v1, v26, v1
	v_cvt_pk_bf16_f32 v1, v1, s0
	ds_write_b16 v48, v1 offset:2368
	v_mul_f32_e32 v1, v11, v0
	v_cvt_pk_bf16_f32 v1, v1, s0
	ds_write_b16 v48, v1 offset:2432
	v_rcp_f32_e32 v1, v44
	v_mul_f32_e32 v0, v27, v0
	v_cvt_pk_bf16_f32 v0, v0, s0
	ds_write_b16 v48, v0 offset:2496
	v_mul_f32_e32 v0, v12, v1
	v_cvt_pk_bf16_f32 v0, v0, s0
	ds_write_b16 v48, v0 offset:3072
	v_rcp_f32_e32 v0, v45
	v_mul_f32_e32 v1, v28, v1
	v_cvt_pk_bf16_f32 v1, v1, s0
	ds_write_b16 v48, v1 offset:3136
	v_mul_f32_e32 v1, v13, v0
	v_cvt_pk_bf16_f32 v1, v1, s0
	ds_write_b16 v48, v1 offset:3200
	v_rcp_f32_e32 v1, v46
	v_mul_f32_e32 v0, v29, v0
	v_cvt_pk_bf16_f32 v0, v0, s0
	ds_write_b16 v48, v0 offset:3264
	v_mul_f32_e32 v0, v14, v1
	v_cvt_pk_bf16_f32 v0, v0, s0
	ds_write_b16 v48, v0 offset:3328
	v_rcp_f32_e32 v0, v47
	v_mul_f32_e32 v1, v30, v1
	v_cvt_pk_bf16_f32 v1, v1, s0
	ds_write_b16 v48, v1 offset:3392
	v_mul_f32_e32 v1, v15, v0
	v_mul_f32_e32 v0, v31, v0
	v_cvt_pk_bf16_f32 v0, v0, s0
	v_add_u32_e32 v10, s24, v172
	v_cvt_pk_bf16_f32 v1, v1, s0
	ds_write_b16 v48, v0 offset:3520
	v_add_u32_e32 v0, v10, v188
	ds_write_b16 v48, v1 offset:3456
	ds_read_b128 v[0:3], v0
	v_or_b32_e32 v4, s27, v187
	v_ashrrev_i32_e32 v5, 31, v4
	v_lshlrev_b64 v[4:5], 11, v[4:5]
	v_lshl_add_u64 v[4:5], s[40:41], 0, v[4:5]
	v_mov_b32_e32 v173, v195
	v_lshl_add_u64 v[8:9], v[4:5], 0, v[172:173]
	v_add_u32_e32 v4, v10, v190
	ds_read_b128 v[4:7], v4
	s_waitcnt lgkmcnt(1)
	global_store_dwordx4 v[8:9], v[0:3], off sc0 sc1
	s_add_i32 s26, s26, s58
	v_readlane_b32 s24, v254, 23
	v_or_b32_e32 v0, s27, v189
	v_ashrrev_i32_e32 v1, 31, v0
	v_lshlrev_b64 v[0:1], 11, v[0:1]
	v_lshl_add_u64 v[0:1], s[40:41], 0, v[0:1]
	v_lshl_add_u64 v[0:1], v[0:1], 0, v[172:173]
	s_waitcnt lgkmcnt(0)
	global_store_dwordx4 v[0:1], v[4:7], off sc0 sc1
	v_add_u32_e32 v0, v10, v196
	ds_read_b128 v[0:3], v0
	v_or_b32_e32 v4, s27, v191
	v_ashrrev_i32_e32 v5, 31, v4
	v_lshlrev_b64 v[4:5], 11, v[4:5]
	v_lshl_add_u64 v[4:5], s[40:41], 0, v[4:5]
	v_lshl_add_u64 v[8:9], v[4:5], 0, v[172:173]
	v_add_u32_e32 v4, v10, v199
	ds_read_b128 v[4:7], v4
	s_waitcnt lgkmcnt(1)
	global_store_dwordx4 v[8:9], v[0:3], off sc0 sc1
	v_readlane_b32 s70, v255, 6
	s_cmp_ge_i32 s26, s24
	v_or_b32_e32 v0, s27, v198
	v_ashrrev_i32_e32 v1, 31, v0
	v_lshlrev_b64 v[0:1], 11, v[0:1]
	v_lshl_add_u64 v[0:1], s[40:41], 0, v[0:1]
	v_lshl_add_u64 v[0:1], v[0:1], 0, v[172:173]
	v_readlane_b32 s71, v255, 7
	s_waitcnt lgkmcnt(0)
	global_store_dwordx4 v[0:1], v[4:7], off sc0 sc1
	s_barrier
	s_cbranch_scc1 .LBB0_202

; #define LAS __attribute__((address_space(3)))
; #define GASA __attribute__((address_space(1)))
; DI unsigned pk2(float lo, float hi) { f32x2 v = {lo, hi}; bf16x2_t b = __builtin_convertvector(v, bf16x2_t); return __builtin_bit_cast(unsigned, b); }
; template <int DQK, int DV, bool BAND>
; DI void attn_unit(const AttnArgs& a, LAS unsigned char* lds, int tid) {
;     ...
;     asm volatile("s_waitcnt lgkmcnt(0)\n\ts_barrier" ::: "memory");
;     __builtin_amdgcn_s_setprio(0);
;     { if (a.lse != nullptr) {
;           if (hi == 0) scr[r32] = m_run;
; #pragma unroll
;           for (int g = 0; g < 4; ++g) { const f32x4 mr = *(const LAS f32x4*)(scr + 8 * g + 4 * hi);
; #pragma unroll
;               for (int e = 0; e < 4; ++e) if (r32 == 0) ((GASA float*)a.lse)[(long)(wid * 32 + 8 * g + 4 * hi + e) * a.lses] = mr[e] + __builtin_amdgcn_logf(lacc[4 * g + e]); } }
;       LAS bf16_t* stg = (LAS bf16_t*)(lds + wid * 8192);
; #pragma unroll
;       for (int g = 0; g < 4; ++g) {
; #pragma unroll
;           for (int e = 0; e < 4; ++e) { const int orow = 8 * g + 4 * hi + e; const float rr = __builtin_amdgcn_rcpf(lacc[4 * g + e]);
; #pragma unroll
;               for (int d = 0; d < NDB; ++d) stg[orow * DV + d * 32 + r32] = (bf16_t)(pk2(o[d][4 * g + e] * rr, 0.f) & 0xffffu); } }
.LBB0_207:
	s_lshl_b64 s[26:27], s[42:43], 12
	s_add_u32 s24, s12, s26
	s_addc_u32 s34, s13, s27
	s_lshl_b32 s26, s18, 7
	s_ashr_i32 s27, s26, 31
	s_waitcnt lgkmcnt(0)
	s_barrier
	v_add_f32_e32 v64, v64, v65
	s_nop 0
	v_mov_b32_e32 v65, v64
	s_nop 1
	v_permlane32_swap_b32_e32 v64, v65
	s_nop 1
	v_add_f32_e32 v64, v64, v65
	ds_write_b32 v185, v64
	s_waitcnt lgkmcnt(0)
	ds_read_b128 v[64:67], v187
	ds_read_b128 v[68:71], v187 offset:32
	ds_read_b128 v[72:75], v187 offset:64
	ds_read_b128 v[76:79], v187 offset:96
	s_waitcnt lgkmcnt(0)
	s_lshl_b64 s[26:27], s[26:27], 1
	s_add_u32 s40, s24, s26
	s_addc_u32 s41, s34, s27
	s_setprio 0
	s_nop 1
	v_rcp_f32_e32 v64, v64
	s_lshl_b32 s18, s19, 13
	s_add_i32 s18, s18, 0
	v_lshlrev_b32_e32 v80, 1, v196
	v_mul_f32_e32 v0, v0, v64
	v_add3_u32 v80, s18, v80, v204
	v_cvt_pk_bf16_f32 v0, v0, s0
	ds_write_b16 v80, v0
	v_mul_f32_e32 v0, v48, v64
	v_cvt_pk_bf16_f32 v0, v0, s0
	ds_write_b16 v80, v0 offset:64
	v_mul_f32_e32 v0, v32, v64
	v_cvt_pk_bf16_f32 v0, v0, s0
	ds_write_b16 v80, v0 offset:128
	v_rcp_f32_e32 v0, v65
	v_mul_f32_e32 v16, v16, v64
	v_cvt_pk_bf16_f32 v16, v16, s0
	ds_write_b16 v80, v16 offset:192
	v_mul_f32_e32 v1, v1, v0
	v_cvt_pk_bf16_f32 v1, v1, s0
	ds_write_b16 v80, v1 offset:256
	v_mul_f32_e32 v1, v49, v0
	v_cvt_pk_bf16_f32 v1, v1, s0
	ds_write_b16 v80, v1 offset:320
	v_mul_f32_e32 v1, v33, v0
	v_cvt_pk_bf16_f32 v1, v1, s0
	ds_write_b16 v80, v1 offset:384
	v_rcp_f32_e32 v1, v66
	v_mul_f32_e32 v0, v17, v0
	v_cvt_pk_bf16_f32 v0, v0, s0
	ds_write_b16 v80, v0 offset:448
	v_mul_f32_e32 v0, v2, v1
	v_cvt_pk_bf16_f32 v0, v0, s0
	ds_write_b16 v80, v0 offset:512
	v_mul_f32_e32 v0, v50, v1
	v_cvt_pk_bf16_f32 v0, v0, s0
	ds_write_b16 v80, v0 offset:576
	v_mul_f32_e32 v0, v34, v1
	v_cvt_pk_bf16_f32 v0, v0, s0
	ds_write_b16 v80, v0 offset:640
	v_rcp_f32_e32 v0, v67
	v_mul_f32_e32 v1, v18, v1
	v_cvt_pk_bf16_f32 v1, v1, s0
	ds_write_b16 v80, v1 offset:704
	v_mul_f32_e32 v1, v3, v0
	v_cvt_pk_bf16_f32 v1, v1, s0
	ds_write_b16 v80, v1 offset:768
	v_mul_f32_e32 v1, v51, v0
	v_cvt_pk_bf16_f32 v1, v1, s0
	ds_write_b16 v80, v1 offset:832
	v_mul_f32_e32 v1, v35, v0
	v_cvt_pk_bf16_f32 v1, v1, s0
	ds_write_b16 v80, v1 offset:896
	v_rcp_f32_e32 v1, v68
	v_mul_f32_e32 v0, v19, v0
	v_cvt_pk_bf16_f32 v0, v0, s0
	ds_write_b16 v80, v0 offset:960
	v_mul_f32_e32 v0, v4, v1
	v_cvt_pk_bf16_f32 v0, v0, s0
	ds_write_b16 v80, v0 offset:2048
	v_mul_f32_e32 v0, v52, v1
	v_cvt_pk_bf16_f32 v0, v0, s0
	ds_write_b16 v80, v0 offset:2112
	v_mul_f32_e32 v0, v36, v1
	v_cvt_pk_bf16_f32 v0, v0, s0
	ds_write_b16 v80, v0 offset:2176
	v_rcp_f32_e32 v0, v69
	v_mul_f32_e32 v1, v20, v1
	v_cvt_pk_bf16_f32 v1, v1, s0
	ds_write_b16 v80, v1 offset:2240
	v_mul_f32_e32 v1, v5, v0
	v_cvt_pk_bf16_f32 v1, v1, s0
	ds_write_b16 v80, v1 offset:2304
	v_mul_f32_e32 v1, v53, v0
	v_cvt_pk_bf16_f32 v1, v1, s0
	ds_write_b16 v80, v1 offset:2368
	v_mul_f32_e32 v1, v37, v0
	v_cvt_pk_bf16_f32 v1, v1, s0
	ds_write_b16 v80, v1 offset:2432
	v_rcp_f32_e32 v1, v70
	v_mul_f32_e32 v0, v21, v0
	v_cvt_pk_bf16_f32 v0, v0, s0
	ds_write_b16 v80, v0 offset:2496
	v_mul_f32_e32 v0, v6, v1
	v_cvt_pk_bf16_f32 v0, v0, s0
	ds_write_b16 v80, v0 offset:2560
	v_mul_f32_e32 v0, v54, v1
	v_cvt_pk_bf16_f32 v0, v0, s0
	ds_write_b16 v80, v0 offset:2624
	v_mul_f32_e32 v0, v38, v1
	v_cvt_pk_bf16_f32 v0, v0, s0
	ds_write_b16 v80, v0 offset:2688
	v_rcp_f32_e32 v0, v71
	v_mul_f32_e32 v1, v22, v1
	v_cvt_pk_bf16_f32 v1, v1, s0
	ds_write_b16 v80, v1 offset:2752
	v_mul_f32_e32 v1, v7, v0
	v_cvt_pk_bf16_f32 v1, v1, s0
	ds_write_b16 v80, v1 offset:2816
	v_mul_f32_e32 v1, v55, v0
	v_cvt_pk_bf16_f32 v1, v1, s0
	ds_write_b16 v80, v1 offset:2880
	v_mul_f32_e32 v1, v39, v0
	v_cvt_pk_bf16_f32 v1, v1, s0
	ds_write_b16 v80, v1 offset:2944
	v_rcp_f32_e32 v1, v72
	v_mul_f32_e32 v0, v23, v0
	v_cvt_pk_bf16_f32 v0, v0, s0
	ds_write_b16 v80, v0 offset:3008
	v_mul_f32_e32 v0, v8, v1
	v_cvt_pk_bf16_f32 v0, v0, s0
	ds_write_b16 v80, v0 offset:4096
	v_mul_f32_e32 v0, v56, v1
	v_cvt_pk_bf16_f32 v0, v0, s0
	ds_write_b16 v80, v0 offset:4160
	v_mul_f32_e32 v0, v40, v1
	v_cvt_pk_bf16_f32 v0, v0, s0
	ds_write_b16 v80, v0 offset:4224
	v_rcp_f32_e32 v0, v73
	v_mul_f32_e32 v1, v24, v1
	v_cvt_pk_bf16_f32 v1, v1, s0
	ds_write_b16 v80, v1 offset:4288
	v_mul_f32_e32 v1, v9, v0
	v_cvt_pk_bf16_f32 v1, v1, s0
	ds_write_b16 v80, v1 offset:4352
	v_mul_f32_e32 v1, v57, v0
	v_cvt_pk_bf16_f32 v1, v1, s0
	ds_write_b16 v80, v1 offset:4416
	v_mul_f32_e32 v1, v41, v0
	v_cvt_pk_bf16_f32 v1, v1, s0
	ds_write_b16 v80, v1 offset:4480
	v_rcp_f32_e32 v1, v74
	v_mul_f32_e32 v0, v25, v0
	v_cvt_pk_bf16_f32 v0, v0, s0
	ds_write_b16 v80, v0 offset:4544
	v_mul_f32_e32 v0, v10, v1
	v_cvt_pk_bf16_f32 v0, v0, s0
	ds_write_b16 v80, v0 offset:4608
	v_mul_f32_e32 v0, v58, v1
	v_cvt_pk_bf16_f32 v0, v0, s0
	ds_write_b16 v80, v0 offset:4672
; #define LAS __attribute__((address_space(3)))
; #define GASA __attribute__((address_space(1)))
; DI unsigned pk2(float lo, float hi) { f32x2 v = {lo, hi}; bf16x2_t b = __builtin_convertvector(v, bf16x2_t); return __builtin_bit_cast(unsigned, b); }
; template <int DQK, int DV, bool BAND>
; DI void attn_unit(const AttnArgs& a, LAS unsigned char* lds, int tid) {
;     ...
;       LAS bf16_t* stg = (LAS bf16_t*)(lds + wid * 8192);
; #pragma unroll
;       for (int g = 0; g < 4; ++g) {
; #pragma unroll
;           for (int e = 0; e < 4; ++e) { const int orow = 8 * g + 4 * hi + e; const float rr = __builtin_amdgcn_rcpf(lacc[4 * g + e]);
; #pragma unroll
;               for (int d = 0; d < NDB; ++d) stg[orow * DV + d * 32 + r32] = (bf16_t)(pk2(o[d][4 * g + e] * rr, 0.f) & 0xffffu); } }
;       constexpr int CPR = DV / 8, RPI = 64 / CPR;
; #pragma unroll
;       for (int i = 0; i < 32 / RPI; ++i) { const int row = i * RPI + lane / CPR, ch = lane % CPR;
;           const u32x4 v = *(const LAS u32x4*)(stg + row * DV + ch * 8); *(GASA u32x4*)((GASA bf16_t*)a.o + (long)(wid * 32 + row) * a.os + ch * 8) = v; }
	v_mul_f32_e32 v0, v42, v1
	v_cvt_pk_bf16_f32 v0, v0, s0
	ds_write_b16 v80, v0 offset:4736
	v_rcp_f32_e32 v0, v75
	v_mul_f32_e32 v1, v26, v1
	v_cvt_pk_bf16_f32 v1, v1, s0
	ds_write_b16 v80, v1 offset:4800
	v_mul_f32_e32 v1, v11, v0
	v_cvt_pk_bf16_f32 v1, v1, s0
	ds_write_b16 v80, v1 offset:4864
	v_mul_f32_e32 v1, v59, v0
	v_cvt_pk_bf16_f32 v1, v1, s0
	ds_write_b16 v80, v1 offset:4928
	v_mul_f32_e32 v1, v43, v0
	v_cvt_pk_bf16_f32 v1, v1, s0
	ds_write_b16 v80, v1 offset:4992
	v_rcp_f32_e32 v1, v76
	v_mul_f32_e32 v0, v27, v0
	v_cvt_pk_bf16_f32 v0, v0, s0
	ds_write_b16 v80, v0 offset:5056
	v_mul_f32_e32 v0, v12, v1
	v_cvt_pk_bf16_f32 v0, v0, s0
	ds_write_b16 v80, v0 offset:6144
	v_mul_f32_e32 v0, v60, v1
	v_cvt_pk_bf16_f32 v0, v0, s0
	ds_write_b16 v80, v0 offset:6208
	v_mul_f32_e32 v0, v44, v1
	v_cvt_pk_bf16_f32 v0, v0, s0
	ds_write_b16 v80, v0 offset:6272
	v_rcp_f32_e32 v0, v77
	v_mul_f32_e32 v1, v28, v1
	v_cvt_pk_bf16_f32 v1, v1, s0
	ds_write_b16 v80, v1 offset:6336
	v_mul_f32_e32 v1, v13, v0
	v_cvt_pk_bf16_f32 v1, v1, s0
	ds_write_b16 v80, v1 offset:6400
	v_mul_f32_e32 v1, v61, v0
	v_cvt_pk_bf16_f32 v1, v1, s0
	ds_write_b16 v80, v1 offset:6464
	v_mul_f32_e32 v1, v45, v0
	v_cvt_pk_bf16_f32 v1, v1, s0
	ds_write_b16 v80, v1 offset:6528
	v_rcp_f32_e32 v1, v78
	v_mul_f32_e32 v0, v29, v0
	v_cvt_pk_bf16_f32 v0, v0, s0
	ds_write_b16 v80, v0 offset:6592
	v_mul_f32_e32 v0, v14, v1
	v_cvt_pk_bf16_f32 v0, v0, s0
	ds_write_b16 v80, v0 offset:6656
	v_mul_f32_e32 v0, v62, v1
	v_cvt_pk_bf16_f32 v0, v0, s0
	ds_write_b16 v80, v0 offset:6720
	v_mul_f32_e32 v0, v46, v1
	v_cvt_pk_bf16_f32 v0, v0, s0
	ds_write_b16 v80, v0 offset:6784
	v_rcp_f32_e32 v0, v79
	v_mul_f32_e32 v1, v30, v1
	v_cvt_pk_bf16_f32 v1, v1, s0
	ds_write_b16 v80, v1 offset:6848
	v_mul_f32_e32 v1, v15, v0
	v_cvt_pk_bf16_f32 v1, v1, s0
	ds_write_b16 v80, v1 offset:6912
	v_mul_f32_e32 v1, v63, v0
	v_cvt_pk_bf16_f32 v1, v1, s0
	ds_write_b16 v80, v1 offset:6976
	v_mul_f32_e32 v1, v47, v0
	v_mul_f32_e32 v0, v31, v0
	v_cvt_pk_bf16_f32 v0, v0, s0
	v_add_u32_e32 v10, s18, v188
	v_cvt_pk_bf16_f32 v1, v1, s0
	ds_write_b16 v80, v0 offset:7104
	v_add_u32_e32 v0, v10, v209
	ds_write_b16 v80, v1 offset:7040
	ds_read_b128 v[0:3], v0
	v_or_b32_e32 v4, s17, v208
	v_ashrrev_i32_e32 v5, 31, v4
	v_lshlrev_b64 v[4:5], 12, v[4:5]
	v_lshl_add_u64 v[4:5], s[40:41], 0, v[4:5]
	v_mov_b32_e32 v189, v195
	v_lshl_add_u64 v[8:9], v[4:5], 0, v[188:189]
	v_add_u32_e32 v4, v10, v211
	ds_read_b128 v[4:7], v4
	s_waitcnt lgkmcnt(1)
	global_store_dwordx4 v[8:9], v[0:3], off sc0 sc1
	s_add_i32 s16, s16, s58
	s_nop 0
	v_or_b32_e32 v0, s17, v210
	v_ashrrev_i32_e32 v1, 31, v0
	v_lshlrev_b64 v[0:1], 12, v[0:1]
	v_lshl_add_u64 v[0:1], s[40:41], 0, v[0:1]
	v_lshl_add_u64 v[0:1], v[0:1], 0, v[188:189]
	s_waitcnt lgkmcnt(0)
	global_store_dwordx4 v[0:1], v[4:7], off sc0 sc1
	v_add_u32_e32 v0, v10, v213
	ds_read_b128 v[0:3], v0
	v_or_b32_e32 v4, s17, v212
	v_ashrrev_i32_e32 v5, 31, v4
	v_lshlrev_b64 v[4:5], 12, v[4:5]
	v_lshl_add_u64 v[4:5], s[40:41], 0, v[4:5]
	v_lshl_add_u64 v[8:9], v[4:5], 0, v[188:189]
	v_add_u32_e32 v4, v10, v215
	ds_read_b128 v[4:7], v4
	s_waitcnt lgkmcnt(1)
	global_store_dwordx4 v[8:9], v[0:3], off sc0 sc1
	s_nop 1
	v_or_b32_e32 v0, s17, v214
	v_ashrrev_i32_e32 v1, 31, v0
	v_lshlrev_b64 v[0:1], 12, v[0:1]
	v_lshl_add_u64 v[0:1], s[40:41], 0, v[0:1]
	v_lshl_add_u64 v[0:1], v[0:1], 0, v[188:189]
	s_waitcnt lgkmcnt(0)
	global_store_dwordx4 v[0:1], v[4:7], off sc0 sc1
	v_add_u32_e32 v0, v10, v217
	ds_read_b128 v[0:3], v0
	v_or_b32_e32 v4, s17, v216
	v_ashrrev_i32_e32 v5, 31, v4
	v_lshlrev_b64 v[4:5], 12, v[4:5]
	v_lshl_add_u64 v[4:5], s[40:41], 0, v[4:5]
	v_lshl_add_u64 v[8:9], v[4:5], 0, v[188:189]
	v_add_u32_e32 v4, v10, v219
	ds_read_b128 v[4:7], v4
	s_waitcnt lgkmcnt(1)
	global_store_dwordx4 v[8:9], v[0:3], off sc0 sc1
	s_nop 1
	v_or_b32_e32 v0, s17, v218
	v_ashrrev_i32_e32 v1, 31, v0
	v_lshlrev_b64 v[0:1], 12, v[0:1]
	v_lshl_add_u64 v[0:1], s[40:41], 0, v[0:1]
	v_lshl_add_u64 v[0:1], v[0:1], 0, v[188:189]
	s_waitcnt lgkmcnt(0)
	global_store_dwordx4 v[0:1], v[4:7], off sc0 sc1
	v_add_u32_e32 v0, v10, v221
	ds_read_b128 v[0:3], v0
	v_or_b32_e32 v4, s17, v220
	v_ashrrev_i32_e32 v5, 31, v4
	v_lshlrev_b64 v[4:5], 12, v[4:5]
	v_lshl_add_u64 v[4:5], s[40:41], 0, v[4:5]
	v_lshl_add_u64 v[8:9], v[4:5], 0, v[188:189]
	v_add_u32_e32 v4, v10, v223
	ds_read_b128 v[4:7], v4
	s_waitcnt lgkmcnt(1)
	global_store_dwordx4 v[8:9], v[0:3], off sc0 sc1
	s_nop 1
	v_or_b32_e32 v0, s17, v222
	v_ashrrev_i32_e32 v1, 31, v0
	v_lshlrev_b64 v[0:1], 12, v[0:1]
	v_lshl_add_u64 v[0:1], s[40:41], 0, v[0:1]
	v_readlane_b32 s17, v254, 23
	v_lshl_add_u64 v[0:1], v[0:1], 0, v[188:189]
	s_cmp_ge_i32 s16, s17
	s_waitcnt lgkmcnt(0)
	global_store_dwordx4 v[0:1], v[4:7], off sc0 sc1
	s_barrier
	s_cbranch_scc1 .LBB0_230

; #define LAS __attribute__((address_space(3)))
; #define GASA __attribute__((address_space(1)))
; DI unsigned pk2(float lo, float hi) { f32x2 v = {lo, hi}; bf16x2_t b = __builtin_convertvector(v, bf16x2_t); return __builtin_bit_cast(unsigned, b); }
; template <int DQK, int DV, bool BAND>
; DI void attn_unit(const AttnArgs& a, LAS unsigned char* lds, int tid) {
;     ...
;     asm volatile("s_waitcnt lgkmcnt(0)\n\ts_barrier" ::: "memory");
;     __builtin_amdgcn_s_setprio(0);
;     { if (a.lse != nullptr) {
;           if (hi == 0) scr[r32] = m_run;
; #pragma unroll
;           for (int g = 0; g < 4; ++g) { const f32x4 mr = *(const LAS f32x4*)(scr + 8 * g + 4 * hi);
; #pragma unroll
;               for (int e = 0; e < 4; ++e) if (r32 == 0) ((GASA float*)a.lse)[(long)(wid * 32 + 8 * g + 4 * hi + e) * a.lses] = mr[e] + __builtin_amdgcn_logf(lacc[4 * g + e]); } }
;       LAS bf16_t* stg = (LAS bf16_t*)(lds + wid * 8192);
; #pragma unroll
;       for (int g = 0; g < 4; ++g) {
; #pragma unroll
;           for (int e = 0; e < 4; ++e) { const int orow = 8 * g + 4 * hi + e; const float rr = __builtin_amdgcn_rcpf(lacc[4 * g + e]);
; #pragma unroll
;               for (int d = 0; d < NDB; ++d) stg[orow * DV + d * 32 + r32] = (bf16_t)(pk2(o[d][4 * g + e] * rr, 0.f) & 0xffffu); } }
;       constexpr int CPR = DV / 8, RPI = 64 / CPR;
; #pragma unroll
;       for (int i = 0; i < 32 / RPI; ++i) { const int row = i * RPI + lane / CPR, ch = lane % CPR;
;           const u32x4 v = *(const LAS u32x4*)(stg + row * DV + ch * 8); *(GASA u32x4*)((GASA bf16_t*)a.o + (long)(wid * 32 + row) * a.os + ch * 8) = v; }
.LBB0_234:
	s_lshl_b64 s[18:19], s[42:43], 11
	s_add_u32 s17, s72, s18
	s_waitcnt lgkmcnt(0)
	s_barrier
	s_addc_u32 s18, s73, s19
	s_add_u32 s40, s17, s46
	s_addc_u32 s41, s18, s47
	s_setprio 0
	s_nop 4
	v_add_f32_e32 v32, v32, v33
	s_nop 0
	v_mov_b32_e32 v33, v32
	s_nop 1
	v_permlane32_swap_b32_e32 v32, v33
	s_nop 1
	v_add_f32_e32 v32, v32, v33
	ds_write_b32 v151, v32
	s_waitcnt lgkmcnt(0)
	ds_read_b128 v[32:35], v153
	ds_read_b128 v[36:39], v153 offset:32
	ds_read_b128 v[40:43], v153 offset:64
	ds_read_b128 v[44:47], v153 offset:96
	s_waitcnt lgkmcnt(0)
	v_rcp_f32_e32 v32, v32
	s_lshl_b32 s16, s16, 13
	s_add_i32 s16, s16, 0
	v_lshlrev_b32_e32 v48, 1, v160
	v_mul_f32_e32 v0, v0, v32
	v_add3_u32 v48, s16, v48, v165
	v_cvt_pk_bf16_f32 v0, v0, s0
	ds_write_b16 v48, v0
	v_rcp_f32_e32 v0, v33
	v_mul_f32_e32 v16, v16, v32
	v_cvt_pk_bf16_f32 v16, v16, s0
	ds_write_b16 v48, v16 offset:64
	v_mul_f32_e32 v1, v1, v0
	v_cvt_pk_bf16_f32 v1, v1, s0
	ds_write_b16 v48, v1 offset:128
	v_rcp_f32_e32 v1, v34
	v_mul_f32_e32 v0, v17, v0
	v_cvt_pk_bf16_f32 v0, v0, s0
	ds_write_b16 v48, v0 offset:192
	v_mul_f32_e32 v0, v2, v1
	v_cvt_pk_bf16_f32 v0, v0, s0
	ds_write_b16 v48, v0 offset:256
	v_rcp_f32_e32 v0, v35
	v_mul_f32_e32 v1, v18, v1
	v_cvt_pk_bf16_f32 v1, v1, s0
	ds_write_b16 v48, v1 offset:320
	v_mul_f32_e32 v1, v3, v0
	v_cvt_pk_bf16_f32 v1, v1, s0
	ds_write_b16 v48, v1 offset:384
	v_rcp_f32_e32 v1, v36
	v_mul_f32_e32 v0, v19, v0
	v_cvt_pk_bf16_f32 v0, v0, s0
	ds_write_b16 v48, v0 offset:448
	v_mul_f32_e32 v0, v4, v1
	v_cvt_pk_bf16_f32 v0, v0, s0
	ds_write_b16 v48, v0 offset:1024
	v_rcp_f32_e32 v0, v37
	v_mul_f32_e32 v1, v20, v1
	v_cvt_pk_bf16_f32 v1, v1, s0
	ds_write_b16 v48, v1 offset:1088
	v_mul_f32_e32 v1, v5, v0
	v_cvt_pk_bf16_f32 v1, v1, s0
	ds_write_b16 v48, v1 offset:1152
	v_rcp_f32_e32 v1, v38
	v_mul_f32_e32 v0, v21, v0
	v_cvt_pk_bf16_f32 v0, v0, s0
	ds_write_b16 v48, v0 offset:1216
	v_mul_f32_e32 v0, v6, v1
	v_cvt_pk_bf16_f32 v0, v0, s0
	ds_write_b16 v48, v0 offset:1280
	v_rcp_f32_e32 v0, v39
	v_mul_f32_e32 v1, v22, v1
	v_cvt_pk_bf16_f32 v1, v1, s0
	ds_write_b16 v48, v1 offset:1344
	v_mul_f32_e32 v1, v7, v0
	v_cvt_pk_bf16_f32 v1, v1, s0
	ds_write_b16 v48, v1 offset:1408
	v_rcp_f32_e32 v1, v40
	v_mul_f32_e32 v0, v23, v0
	v_cvt_pk_bf16_f32 v0, v0, s0
	ds_write_b16 v48, v0 offset:1472
	v_mul_f32_e32 v0, v8, v1
	v_cvt_pk_bf16_f32 v0, v0, s0
	ds_write_b16 v48, v0 offset:2048
	v_rcp_f32_e32 v0, v41
	v_mul_f32_e32 v1, v24, v1
	v_cvt_pk_bf16_f32 v1, v1, s0
	ds_write_b16 v48, v1 offset:2112
	v_mul_f32_e32 v1, v9, v0
	v_cvt_pk_bf16_f32 v1, v1, s0
	ds_write_b16 v48, v1 offset:2176
	v_rcp_f32_e32 v1, v42
	v_mul_f32_e32 v0, v25, v0
	v_cvt_pk_bf16_f32 v0, v0, s0
	ds_write_b16 v48, v0 offset:2240
	v_mul_f32_e32 v0, v10, v1
	v_cvt_pk_bf16_f32 v0, v0, s0
	ds_write_b16 v48, v0 offset:2304
	v_rcp_f32_e32 v0, v43
	v_mul_f32_e32 v1, v26, v1
	v_cvt_pk_bf16_f32 v1, v1, s0
	ds_write_b16 v48, v1 offset:2368
	v_mul_f32_e32 v1, v11, v0
	v_cvt_pk_bf16_f32 v1, v1, s0
	ds_write_b16 v48, v1 offset:2432
	v_rcp_f32_e32 v1, v44
	v_mul_f32_e32 v0, v27, v0
	v_cvt_pk_bf16_f32 v0, v0, s0
	ds_write_b16 v48, v0 offset:2496
	v_mul_f32_e32 v0, v12, v1
	v_cvt_pk_bf16_f32 v0, v0, s0
	ds_write_b16 v48, v0 offset:3072
	v_rcp_f32_e32 v0, v45
	v_mul_f32_e32 v1, v28, v1
	v_cvt_pk_bf16_f32 v1, v1, s0
	ds_write_b16 v48, v1 offset:3136
	v_mul_f32_e32 v1, v13, v0
	v_cvt_pk_bf16_f32 v1, v1, s0
	ds_write_b16 v48, v1 offset:3200
	v_rcp_f32_e32 v1, v46
	v_mul_f32_e32 v0, v29, v0
	v_cvt_pk_bf16_f32 v0, v0, s0
	ds_write_b16 v48, v0 offset:3264
	v_mul_f32_e32 v0, v14, v1
	v_cvt_pk_bf16_f32 v0, v0, s0
	ds_write_b16 v48, v0 offset:3328
	v_rcp_f32_e32 v0, v47
	v_mul_f32_e32 v1, v30, v1
	v_cvt_pk_bf16_f32 v1, v1, s0
	ds_write_b16 v48, v1 offset:3392
	v_mul_f32_e32 v1, v15, v0
	v_mul_f32_e32 v0, v31, v0
	v_cvt_pk_bf16_f32 v0, v0, s0
	v_add_u32_e32 v10, s16, v154
	v_cvt_pk_bf16_f32 v1, v1, s0
	ds_write_b16 v48, v0 offset:3520
	v_add_u32_e32 v0, v10, v167
	ds_write_b16 v48, v1 offset:3456
	ds_read_b128 v[0:3], v0
	v_or_b32_e32 v4, s13, v166
	v_ashrrev_i32_e32 v5, 31, v4
	v_lshlrev_b64 v[4:5], 11, v[4:5]
	v_lshl_add_u64 v[4:5], s[40:41], 0, v[4:5]
	v_mov_b32_e32 v155, v195
	v_lshl_add_u64 v[8:9], v[4:5], 0, v[154:155]
	v_add_u32_e32 v4, v10, v169
	ds_read_b128 v[4:7], v4
	s_waitcnt lgkmcnt(1)
	global_store_dwordx4 v[8:9], v[0:3], off sc0 sc1
	s_add_i32 s12, s12, s58
	s_nop 0
	v_or_b32_e32 v0, s13, v168
	v_ashrrev_i32_e32 v1, 31, v0
	v_lshlrev_b64 v[0:1], 11, v[0:1]
	v_lshl_add_u64 v[0:1], s[40:41], 0, v[0:1]
	v_lshl_add_u64 v[0:1], v[0:1], 0, v[154:155]
	s_waitcnt lgkmcnt(0)
	global_store_dwordx4 v[0:1], v[4:7], off sc0 sc1
	v_add_u32_e32 v0, v10, v171
	ds_read_b128 v[0:3], v0
	v_or_b32_e32 v4, s13, v170
	v_ashrrev_i32_e32 v5, 31, v4
	v_lshlrev_b64 v[4:5], 11, v[4:5]
	v_lshl_add_u64 v[4:5], s[40:41], 0, v[4:5]
	v_lshl_add_u64 v[8:9], v[4:5], 0, v[154:155]
	v_add_u32_e32 v4, v10, v173
	ds_read_b128 v[4:7], v4
	s_waitcnt lgkmcnt(1)
	global_store_dwordx4 v[8:9], v[0:3], off sc0 sc1
	s_nop 1
	v_or_b32_e32 v0, s13, v172
	v_ashrrev_i32_e32 v1, 31, v0
	v_lshlrev_b64 v[0:1], 11, v[0:1]
	v_lshl_add_u64 v[0:1], s[40:41], 0, v[0:1]
	v_readlane_b32 s13, v254, 23
	v_lshl_add_u64 v[0:1], v[0:1], 0, v[154:155]
	s_cmp_ge_i32 s12, s13
	s_waitcnt lgkmcnt(0)
	global_store_dwordx4 v[0:1], v[4:7], off sc0 sc1
	s_barrier
	s_cbranch_scc1 .LBB0_259

; #define LAS __attribute__((address_space(3)))
; #define GASA __attribute__((address_space(1)))
; DI unsigned pk2(float lo, float hi) { f32x2 v = {lo, hi}; bf16x2_t b = __builtin_convertvector(v, bf16x2_t); return __builtin_bit_cast(unsigned, b); }
; template <int DQK, int DV, bool BAND>
; DI void attn_unit(const AttnArgs& a, LAS unsigned char* lds, int tid) {
;     ...
;       LAS bf16_t* stg = (LAS bf16_t*)(lds + wid * 8192);
; #pragma unroll
;       for (int g = 0; g < 4; ++g) {
; #pragma unroll
;           for (int e = 0; e < 4; ++e) { const int orow = 8 * g + 4 * hi + e; const float rr = __builtin_amdgcn_rcpf(lacc[4 * g + e]);
; #pragma unroll
;               for (int d = 0; d < NDB; ++d) stg[orow * DV + d * 32 + r32] = (bf16_t)(pk2(o[d][4 * g + e] * rr, 0.f) & 0xffffu); } }
;       constexpr int CPR = DV / 8, RPI = 64 / CPR;
; #pragma unroll
;       for (int i = 0; i < 32 / RPI; ++i) { const int row = i * RPI + lane / CPR, ch = lane % CPR;
;           const u32x4 v = *(const LAS u32x4*)(stg + row * DV + ch * 8); *(GASA u32x4*)((GASA bf16_t*)a.o + (long)(wid * 32 + row) * a.os + ch * 8) = v; }
.LBB0_265:
	s_or_b64 exec, exec, s[46:47]
	v_rcp_f32_e32 v0, v0
	v_rcp_f32_e32 v1, v1
	s_lshl_b32 s19, s19, 13
	s_add_i32 s19, s19, 0
	v_lshlrev_b32_e32 v48, 1, v168
	v_mul_f32_e32 v32, v32, v0
	v_mul_f32_e32 v0, v16, v0
	v_add3_u32 v48, s19, v48, v171
	v_cvt_pk_bf16_f32 v0, v0, s0
	ds_write_b16 v48, v0 offset:64
	v_mul_f32_e32 v0, v33, v1
	v_cvt_pk_bf16_f32 v0, v0, s0
	ds_write_b16 v48, v0 offset:128
	v_rcp_f32_e32 v0, v2
	v_mul_f32_e32 v1, v17, v1
	v_cvt_pk_bf16_f32 v1, v1, s0
	ds_write_b16 v48, v1 offset:192
	v_mul_f32_e32 v1, v34, v0
	v_cvt_pk_bf16_f32 v1, v1, s0
	ds_write_b16 v48, v1 offset:256
	v_rcp_f32_e32 v1, v3
	v_mul_f32_e32 v0, v18, v0
	v_cvt_pk_bf16_f32 v0, v0, s0
	ds_write_b16 v48, v0 offset:320
	v_mul_f32_e32 v0, v35, v1
	v_cvt_pk_bf16_f32 v0, v0, s0
	ds_write_b16 v48, v0 offset:384
	v_rcp_f32_e32 v0, v4
	v_mul_f32_e32 v1, v19, v1
	v_cvt_pk_bf16_f32 v1, v1, s0
	ds_write_b16 v48, v1 offset:448
	v_mul_f32_e32 v1, v36, v0
	v_cvt_pk_bf16_f32 v1, v1, s0
	ds_write_b16 v48, v1 offset:1024
	v_rcp_f32_e32 v1, v5
	v_mul_f32_e32 v0, v20, v0
	v_cvt_pk_bf16_f32 v0, v0, s0
	ds_write_b16 v48, v0 offset:1088
	v_mul_f32_e32 v0, v37, v1
	v_cvt_pk_bf16_f32 v0, v0, s0
	ds_write_b16 v48, v0 offset:1152
	v_rcp_f32_e32 v0, v6
	v_mul_f32_e32 v1, v21, v1
	v_cvt_pk_bf16_f32 v1, v1, s0
	ds_write_b16 v48, v1 offset:1216
	v_mul_f32_e32 v1, v38, v0
	v_cvt_pk_bf16_f32 v1, v1, s0
	ds_write_b16 v48, v1 offset:1280
	v_rcp_f32_e32 v1, v7
	v_mul_f32_e32 v0, v22, v0
	v_cvt_pk_bf16_f32 v0, v0, s0
	ds_write_b16 v48, v0 offset:1344
	v_mul_f32_e32 v0, v39, v1
	v_cvt_pk_bf16_f32 v0, v0, s0
	ds_write_b16 v48, v0 offset:1408
	v_rcp_f32_e32 v0, v8
	v_mul_f32_e32 v1, v23, v1
	v_cvt_pk_bf16_f32 v1, v1, s0
	ds_write_b16 v48, v1 offset:1472
	v_mul_f32_e32 v1, v40, v0
	v_cvt_pk_bf16_f32 v1, v1, s0
	ds_write_b16 v48, v1 offset:2048
	v_rcp_f32_e32 v1, v9
	v_mul_f32_e32 v0, v24, v0
	v_cvt_pk_bf16_f32 v0, v0, s0
	ds_write_b16 v48, v0 offset:2112
	v_mul_f32_e32 v0, v41, v1
	v_cvt_pk_bf16_f32 v0, v0, s0
	ds_write_b16 v48, v0 offset:2176
	v_rcp_f32_e32 v0, v10
	v_mul_f32_e32 v1, v25, v1
	v_cvt_pk_bf16_f32 v1, v1, s0
	ds_write_b16 v48, v1 offset:2240
	v_mul_f32_e32 v1, v42, v0
	v_cvt_pk_bf16_f32 v1, v1, s0
	ds_write_b16 v48, v1 offset:2304
	v_rcp_f32_e32 v1, v11
	v_mul_f32_e32 v0, v26, v0
	v_cvt_pk_bf16_f32 v0, v0, s0
	ds_write_b16 v48, v0 offset:2368
	v_mul_f32_e32 v0, v43, v1
	v_cvt_pk_bf16_f32 v0, v0, s0
	ds_write_b16 v48, v0 offset:2432
	v_rcp_f32_e32 v0, v12
	v_mul_f32_e32 v1, v27, v1
	v_cvt_pk_bf16_f32 v1, v1, s0
	ds_write_b16 v48, v1 offset:2496
	v_mul_f32_e32 v1, v44, v0
	v_cvt_pk_bf16_f32 v1, v1, s0
	ds_write_b16 v48, v1 offset:3072
	v_rcp_f32_e32 v1, v13
	v_mul_f32_e32 v0, v28, v0
	v_cvt_pk_bf16_f32 v0, v0, s0
	ds_write_b16 v48, v0 offset:3136
	v_mul_f32_e32 v0, v45, v1
	v_cvt_pk_bf16_f32 v0, v0, s0
	ds_write_b16 v48, v0 offset:3200
	v_rcp_f32_e32 v0, v14
	v_mul_f32_e32 v1, v29, v1
	v_cvt_pk_bf16_f32 v1, v1, s0
	ds_write_b16 v48, v1 offset:3264
	v_mul_f32_e32 v1, v46, v0
	v_cvt_pk_bf16_f32 v1, v1, s0
	ds_write_b16 v48, v1 offset:3328
	v_rcp_f32_e32 v1, v15
	v_mul_f32_e32 v0, v30, v0
	v_cvt_pk_bf16_f32 v0, v0, s0
	ds_write_b16 v48, v0 offset:3392
	v_mul_f32_e32 v0, v47, v1
	v_cvt_pk_bf16_f32 v0, v0, s0
	ds_write_b16 v48, v0 offset:3456
	v_mul_f32_e32 v0, v31, v1
	v_cvt_pk_bf16_f32 v32, v32, s0
	v_cvt_pk_bf16_f32 v0, v0, s0
	v_add_u32_e32 v10, s19, v166
	ds_write_b16 v48, v32
	ds_write_b16 v48, v0 offset:3520
	v_add_u32_e32 v0, v10, v173
	ds_read_b128 v[0:3], v0
	v_or_b32_e32 v4, s18, v172
	v_mad_i64_i32 v[4:5], s[26:27], s17, v4, 0
	v_lshl_add_u64 v[4:5], v[4:5], 1, s[36:37]
	v_mov_b32_e32 v167, v195
	v_lshl_add_u64 v[8:9], v[4:5], 0, v[166:167]
	v_add_u32_e32 v4, v10, v175
	ds_read_b128 v[4:7], v4
	s_waitcnt lgkmcnt(1)
	global_store_dwordx4 v[8:9], v[0:3], off sc0 sc1
	s_add_i32 s16, s16, s58
	s_nop 0
	v_or_b32_e32 v0, s18, v174
	v_mad_i64_i32 v[0:1], s[26:27], s17, v0, 0
	v_lshl_add_u64 v[0:1], v[0:1], 1, s[36:37]
	v_lshl_add_u64 v[0:1], v[0:1], 0, v[166:167]
	s_waitcnt lgkmcnt(0)
	global_store_dwordx4 v[0:1], v[4:7], off sc0 sc1
	v_add_u32_e32 v0, v10, v179
	ds_read_b128 v[0:3], v0
	v_or_b32_e32 v4, s18, v178
	v_mad_i64_i32 v[4:5], s[26:27], s17, v4, 0
	v_lshl_add_u64 v[4:5], v[4:5], 1, s[36:37]
	v_lshl_add_u64 v[8:9], v[4:5], 0, v[166:167]
	v_add_u32_e32 v4, v10, v181
	ds_read_b128 v[4:7], v4
	s_waitcnt lgkmcnt(1)
	global_store_dwordx4 v[8:9], v[0:3], off sc0 sc1
	s_nop 1
	v_or_b32_e32 v0, s18, v180
	v_mad_i64_i32 v[0:1], s[18:19], s17, v0, 0
	v_lshl_add_u64 v[0:1], v[0:1], 1, s[36:37]
	v_readlane_b32 s17, v254, 26
	v_lshl_add_u64 v[0:1], v[0:1], 0, v[166:167]
	s_cmp_ge_i32 s16, s17
	s_waitcnt lgkmcnt(0)
	global_store_dwordx4 v[0:1], v[4:7], off sc0 sc1
	s_barrier
	s_cbranch_scc1 .LBB0_296

; #define PG8_GAS __attribute__((address_space(1)))
;     __device__ __forceinline__ void operator()(const f32x4 (&acc)[2][2][4][2], const Unit& u, int wr, int wc, int fr, int fq) const {
;     ...
;         for (int ai = 0; ai < 2; ++ai)
; #pragma unroll
;             for (int m = 0; m < 4; ++m) { PG8_GAS bf16_t* rowp = (PG8_GAS bf16_t*)O + (size_t)(row0 + ai * HALF + m * 16) * ldc + col0;
;                 const float rs = rsv[ai][m];
; #pragma unroll
;                 for (int bj = 0; bj < 2; ++bj) { f32x4 v0 = acc[ai][bj][m][0] * rs, v1 = acc[ai][bj][m][1] * rs;
;                     if (mode != 0) {
;                         const bool span = mode == 1 ? ((wc & 1) == 0 && (u.pn % rmod) < rlim) : (((u.pn * 8 + bj * 4 + wc) % 3) == 2);
;                         if (span) {
;                             const int pos = (row0 + ai * HALF + m * 16) & smask;
;                             const PG8_GAS f32x4* t4 = (const PG8_GAS f32x4*)((const PG8_GAS float*)tab + (mode == 1 ? (size_t)pos * 16 : (size_t)pos * 32 + 16 * (fq & 1)));
;                             const int dist = mode == 1 ? 16 : 32; const bool part = mode == 1 ? fq < 2 : true; const bool firsth = mode == 1 ? fq == 0 : fq < 2;
;                             const f32x4 c0 = t4[0], c1 = t4[1], c2 = t4[2], c3 = t4[3];
;                             f32x4 o0, o1;
; #pragma unroll
;                             for (int e = 0; e < 4; ++e) { o0[e] = __shfl_xor(v0[e], dist); o1[e] = __shfl_xor(v1[e], dist); }
;                             if (part) { const float sg = firsth ? -1.0f : 1.0f;
;                                 v0[0] = v0[0] * c0.x + sg * o0[0] * c0.y; v0[1] = v0[1] * c0.z + sg * o0[1] * c0.w; v0[2] = v0[2] * c1.x + sg * o0[2] * c1.y; v0[3] = v0[3] * c1.z + sg * o0[3] * c1.w;
;                                 v1[0] = v1[0] * c2.x + sg * o1[0] * c2.y; v1[1] = v1[1] * c2.z + sg * o1[1] * c2.w; v1[2] = v1[2] * c3.x + sg * o1[2] * c3.y; v1[3] = v1[3] * c3.z + sg * o1[3] * c3.w; }
;                         }
;                     }
;                     if (ACT == 1) {
; #pragma unroll
;                         for (int e = 0; e < 4; ++e) { float a = v0[e] > 0.f ? v0[e] : 0.f; v0[e] = a * a; float b = v1[e] > 0.f ? v1[e] : 0.f; v1[e] = b * b; } }
;                     u32x4 w; w.x = cvt_pk_bf16(v0[0], v0[1]); w.y = cvt_pk_bf16(v0[2], v0[3]); w.z = cvt_pk_bf16(v1[0], v1[1]); w.w = cvt_pk_bf16(v1[2], v1[3]);
.LBB0_432:
	v_pk_mul_f32 v[120:121], v[120:121], v[140:141] op_sel_hi:[1,0]
	v_lshl_or_b32 v156, s76, 8, v158
	v_mul_lo_u32 v139, v139, s67
	v_mad_u64_u32 v[160:161], s[40:41], v138, s67, 0
	v_pk_mul_f32 v[124:125], v[124:125], v[140:141] op_sel_hi:[1,0]
	v_pk_mul_f32 v[122:123], v[122:123], v[140:141] op_sel_hi:[1,0]
	v_max_f32_e32 v120, 0, v120
	v_ashrrev_i32_e32 v157, 31, v156
	v_add_u32_e32 v161, v161, v139
	v_pk_mul_f32 v[126:127], v[126:127], v[140:141] op_sel_hi:[1,0]
	v_mul_f32_e32 v145, v120, v120
	v_max_f32_e32 v120, 0, v125
	v_max_f32_e32 v121, 0, v121
	v_max_f32_e32 v122, 0, v122
	v_lshl_add_u64 v[160:161], v[160:161], 1, s[96:97]
	v_lshlrev_b64 v[156:157], 1, v[156:157]
	v_max_f32_e32 v124, 0, v124
	v_mul_f32_e32 v120, v120, v120
	v_mul_f32_e32 v125, v121, v121
	v_max_f32_e32 v121, 0, v126
	v_mul_f32_e32 v126, v122, v122
	v_max_f32_e32 v122, 0, v127
	v_max_f32_e32 v123, 0, v123
	v_pk_mul_f32 v[112:113], v[112:113], v[140:141] op_sel_hi:[1,0]
	v_lshl_add_u64 v[160:161], v[160:161], 0, v[156:157]
	v_mul_f32_e32 v124, v124, v124
	v_mul_f32_e32 v121, v121, v121
	v_mul_f32_e32 v122, v122, v122
	v_mul_f32_e32 v123, v123, v123
	v_cvt_pk_bf16_f32 v120, v124, v120
	v_pk_mul_f32 v[116:117], v[116:117], v[140:141] op_sel_hi:[1,0]
	v_pk_mul_f32 v[114:115], v[114:115], v[140:141] op_sel_hi:[1,0]
	v_max_f32_e32 v112, 0, v112
	v_cvt_pk_bf16_f32 v121, v121, v122
	v_cvt_pk_bf16_f32 v122, v145, v125
	v_cvt_pk_bf16_f32 v123, v126, v123
	global_store_dwordx4 v[160:161], v[120:123], off sc0 sc1
	v_pk_mul_f32 v[118:119], v[118:119], v[140:141] op_sel_hi:[1,0]
	v_max_f32_e32 v113, 0, v113
	v_mul_f32_e32 v120, v112, v112
	v_max_f32_e32 v112, 0, v117
	v_max_f32_e32 v114, 0, v114
	v_max_f32_e32 v116, 0, v116
	v_mul_f32_e32 v112, v112, v112
	v_mul_f32_e32 v117, v113, v113
	v_max_f32_e32 v113, 0, v118
	v_mul_f32_e32 v118, v114, v114
	v_max_f32_e32 v114, 0, v119
	v_max_f32_e32 v115, 0, v115
	v_mul_f32_e32 v116, v116, v116
	v_mul_f32_e32 v113, v113, v113
	v_mul_f32_e32 v114, v114, v114
	v_mul_f32_e32 v115, v115, v115
	v_cvt_pk_bf16_f32 v112, v116, v112
	v_cvt_pk_bf16_f32 v113, v113, v114
	v_cvt_pk_bf16_f32 v114, v120, v117
	v_cvt_pk_bf16_f32 v115, v118, v115
	global_store_dwordx4 v[160:161], v[112:115], off offset:256 sc0 sc1
	v_pk_mul_f32 v[104:105], v[104:105], v[142:143] op_sel_hi:[1,0]
	v_pk_mul_f32 v[108:109], v[108:109], v[142:143] op_sel_hi:[1,0]
	v_or_b32_e32 v112, 16, v138
	v_mad_u64_u32 v[112:113], s[40:41], v112, s67, 0
	v_pk_mul_f32 v[106:107], v[106:107], v[142:143] op_sel_hi:[1,0]
	v_max_f32_e32 v104, 0, v104
	v_add_u32_e32 v113, v113, v139
	v_pk_mul_f32 v[110:111], v[110:111], v[142:143] op_sel_hi:[1,0]
	v_mul_f32_e32 v114, v104, v104
	v_max_f32_e32 v104, 0, v109
	v_max_f32_e32 v105, 0, v105
	v_max_f32_e32 v106, 0, v106
	v_lshl_add_u64 v[112:113], v[112:113], 1, s[96:97]
	v_max_f32_e32 v108, 0, v108
	v_mul_f32_e32 v104, v104, v104
	v_mul_f32_e32 v109, v105, v105
	v_max_f32_e32 v105, 0, v110
	v_mul_f32_e32 v110, v106, v106
	v_max_f32_e32 v106, 0, v111
	v_max_f32_e32 v107, 0, v107
	v_pk_mul_f32 v[96:97], v[96:97], v[142:143] op_sel_hi:[1,0]
	v_lshl_add_u64 v[112:113], v[112:113], 0, v[156:157]
	v_mul_f32_e32 v108, v108, v108
	v_mul_f32_e32 v105, v105, v105
	v_mul_f32_e32 v106, v106, v106
	v_mul_f32_e32 v107, v107, v107
	v_cvt_pk_bf16_f32 v104, v108, v104
	v_pk_mul_f32 v[100:101], v[100:101], v[142:143] op_sel_hi:[1,0]
	v_pk_mul_f32 v[98:99], v[98:99], v[142:143] op_sel_hi:[1,0]
	v_max_f32_e32 v96, 0, v96
	v_cvt_pk_bf16_f32 v105, v105, v106
	v_cvt_pk_bf16_f32 v106, v114, v109
	v_cvt_pk_bf16_f32 v107, v110, v107
	global_store_dwordx4 v[112:113], v[104:107], off sc0 sc1
	v_pk_mul_f32 v[102:103], v[102:103], v[142:143] op_sel_hi:[1,0]
	v_max_f32_e32 v97, 0, v97
	v_mul_f32_e32 v104, v96, v96
	v_max_f32_e32 v96, 0, v101
	v_max_f32_e32 v98, 0, v98
	v_max_f32_e32 v100, 0, v100
	v_mul_f32_e32 v96, v96, v96
	v_mul_f32_e32 v101, v97, v97
	v_max_f32_e32 v97, 0, v102
	v_mul_f32_e32 v102, v98, v98
	v_max_f32_e32 v98, 0, v103
	v_max_f32_e32 v99, 0, v99
	v_mul_f32_e32 v100, v100, v100
	v_mul_f32_e32 v97, v97, v97
	v_mul_f32_e32 v98, v98, v98
	v_mul_f32_e32 v99, v99, v99
	v_cvt_pk_bf16_f32 v96, v100, v96
	v_cvt_pk_bf16_f32 v97, v97, v98
	v_cvt_pk_bf16_f32 v98, v104, v101
	v_cvt_pk_bf16_f32 v99, v102, v99
	global_store_dwordx4 v[112:113], v[96:99], off offset:256 sc0 sc1
	v_pk_mul_f32 v[88:89], v[88:89], v[146:147] op_sel_hi:[1,0]
	v_pk_mul_f32 v[92:93], v[92:93], v[146:147] op_sel_hi:[1,0]
	v_or_b32_e32 v96, 32, v138
	v_mad_u64_u32 v[96:97], s[40:41], v96, s67, 0
	v_pk_mul_f32 v[90:91], v[90:91], v[146:147] op_sel_hi:[1,0]
	v_max_f32_e32 v88, 0, v88
	v_add_u32_e32 v97, v97, v139
	v_pk_mul_f32 v[94:95], v[94:95], v[146:147] op_sel_hi:[1,0]
	v_mul_f32_e32 v98, v88, v88
	v_max_f32_e32 v88, 0, v93
	v_max_f32_e32 v89, 0, v89
	v_max_f32_e32 v90, 0, v90
	v_lshl_add_u64 v[96:97], v[96:97], 1, s[96:97]
	v_max_f32_e32 v92, 0, v92
	v_mul_f32_e32 v88, v88, v88
	v_mul_f32_e32 v93, v89, v89
	v_max_f32_e32 v89, 0, v94
	v_mul_f32_e32 v94, v90, v90
	v_max_f32_e32 v90, 0, v95
	v_max_f32_e32 v91, 0, v91
	v_pk_mul_f32 v[80:81], v[80:81], v[146:147] op_sel_hi:[1,0]
	v_lshl_add_u64 v[96:97], v[96:97], 0, v[156:157]
	v_mul_f32_e32 v92, v92, v92
	v_mul_f32_e32 v89, v89, v89
	v_mul_f32_e32 v90, v90, v90
	v_mul_f32_e32 v91, v91, v91
	v_cvt_pk_bf16_f32 v88, v92, v88
	v_pk_mul_f32 v[84:85], v[84:85], v[146:147] op_sel_hi:[1,0]
	v_pk_mul_f32 v[82:83], v[82:83], v[146:147] op_sel_hi:[1,0]
	v_max_f32_e32 v80, 0, v80
	v_cvt_pk_bf16_f32 v89, v89, v90
	v_cvt_pk_bf16_f32 v90, v98, v93
	v_cvt_pk_bf16_f32 v91, v94, v91
	global_store_dwordx4 v[96:97], v[88:91], off sc0 sc1
; #define PG8_GAS __attribute__((address_space(1)))
;     __device__ __forceinline__ void operator()(const f32x4 (&acc)[2][2][4][2], const Unit& u, int wr, int wc, int fr, int fq) const {
;     ...
;         for (int ai = 0; ai < 2; ++ai)
; #pragma unroll
;             for (int m = 0; m < 4; ++m) { PG8_GAS bf16_t* rowp = (PG8_GAS bf16_t*)O + (size_t)(row0 + ai * HALF + m * 16) * ldc + col0;
;                 const float rs = rsv[ai][m];
; #pragma unroll
;                 for (int bj = 0; bj < 2; ++bj) { f32x4 v0 = acc[ai][bj][m][0] * rs, v1 = acc[ai][bj][m][1] * rs;
;                     if (mode != 0) {
;                         const bool span = mode == 1 ? ((wc & 1) == 0 && (u.pn % rmod) < rlim) : (((u.pn * 8 + bj * 4 + wc) % 3) == 2);
;                         if (span) {
;                             const int pos = (row0 + ai * HALF + m * 16) & smask;
;                             const PG8_GAS f32x4* t4 = (const PG8_GAS f32x4*)((const PG8_GAS float*)tab + (mode == 1 ? (size_t)pos * 16 : (size_t)pos * 32 + 16 * (fq & 1)));
;                             const int dist = mode == 1 ? 16 : 32; const bool part = mode == 1 ? fq < 2 : true; const bool firsth = mode == 1 ? fq == 0 : fq < 2;
;                             const f32x4 c0 = t4[0], c1 = t4[1], c2 = t4[2], c3 = t4[3];
;                             f32x4 o0, o1;
; #pragma unroll
;                             for (int e = 0; e < 4; ++e) { o0[e] = __shfl_xor(v0[e], dist); o1[e] = __shfl_xor(v1[e], dist); }
;                             if (part) { const float sg = firsth ? -1.0f : 1.0f;
;                                 v0[0] = v0[0] * c0.x + sg * o0[0] * c0.y; v0[1] = v0[1] * c0.z + sg * o0[1] * c0.w; v0[2] = v0[2] * c1.x + sg * o0[2] * c1.y; v0[3] = v0[3] * c1.z + sg * o0[3] * c1.w;
;                                 v1[0] = v1[0] * c2.x + sg * o1[0] * c2.y; v1[1] = v1[1] * c2.z + sg * o1[1] * c2.w; v1[2] = v1[2] * c3.x + sg * o1[2] * c3.y; v1[3] = v1[3] * c3.z + sg * o1[3] * c3.w; }
;                         }
;                     }
;                     if (ACT == 1) {
; #pragma unroll
;                         for (int e = 0; e < 4; ++e) { float a = v0[e] > 0.f ? v0[e] : 0.f; v0[e] = a * a; float b = v1[e] > 0.f ? v1[e] : 0.f; v1[e] = b * b; } }
;                     u32x4 w; w.x = cvt_pk_bf16(v0[0], v0[1]); w.y = cvt_pk_bf16(v0[2], v0[3]); w.z = cvt_pk_bf16(v1[0], v1[1]); w.w = cvt_pk_bf16(v1[2], v1[3]);
	v_pk_mul_f32 v[86:87], v[86:87], v[146:147] op_sel_hi:[1,0]
	v_max_f32_e32 v81, 0, v81
	v_mul_f32_e32 v88, v80, v80
	v_max_f32_e32 v80, 0, v85
	v_max_f32_e32 v82, 0, v82
	v_max_f32_e32 v84, 0, v84
	v_mul_f32_e32 v80, v80, v80
	v_mul_f32_e32 v85, v81, v81
	v_max_f32_e32 v81, 0, v86
	v_mul_f32_e32 v86, v82, v82
	v_max_f32_e32 v82, 0, v87
	v_max_f32_e32 v83, 0, v83
	v_mul_f32_e32 v84, v84, v84
	v_mul_f32_e32 v81, v81, v81
	v_mul_f32_e32 v82, v82, v82
	v_mul_f32_e32 v83, v83, v83
	v_cvt_pk_bf16_f32 v80, v84, v80
	v_cvt_pk_bf16_f32 v81, v81, v82
	v_cvt_pk_bf16_f32 v82, v88, v85
	v_cvt_pk_bf16_f32 v83, v86, v83
	global_store_dwordx4 v[96:97], v[80:83], off offset:256 sc0 sc1
	v_pk_mul_f32 v[72:73], v[72:73], v[154:155] op_sel_hi:[1,0]
	v_pk_mul_f32 v[76:77], v[76:77], v[154:155] op_sel_hi:[1,0]
	v_or_b32_e32 v80, 48, v138
	v_mad_u64_u32 v[80:81], s[40:41], v80, s67, 0
	v_pk_mul_f32 v[74:75], v[74:75], v[154:155] op_sel_hi:[1,0]
	v_max_f32_e32 v72, 0, v72
	v_add_u32_e32 v81, v81, v139
	v_pk_mul_f32 v[78:79], v[78:79], v[154:155] op_sel_hi:[1,0]
	v_mul_f32_e32 v82, v72, v72
	v_max_f32_e32 v72, 0, v77
	v_max_f32_e32 v73, 0, v73
	v_max_f32_e32 v74, 0, v74
	v_lshl_add_u64 v[80:81], v[80:81], 1, s[96:97]
	v_max_f32_e32 v76, 0, v76
	v_mul_f32_e32 v72, v72, v72
	v_mul_f32_e32 v77, v73, v73
	v_max_f32_e32 v73, 0, v78
	v_mul_f32_e32 v78, v74, v74
	v_max_f32_e32 v74, 0, v79
	v_max_f32_e32 v75, 0, v75
	v_pk_mul_f32 v[64:65], v[64:65], v[154:155] op_sel_hi:[1,0]
	v_lshl_add_u64 v[80:81], v[80:81], 0, v[156:157]
	v_mul_f32_e32 v76, v76, v76
	v_mul_f32_e32 v73, v73, v73
	v_mul_f32_e32 v74, v74, v74
	v_mul_f32_e32 v75, v75, v75
	v_cvt_pk_bf16_f32 v72, v76, v72
	v_pk_mul_f32 v[68:69], v[68:69], v[154:155] op_sel_hi:[1,0]
	v_pk_mul_f32 v[66:67], v[66:67], v[154:155] op_sel_hi:[1,0]
	v_max_f32_e32 v64, 0, v64
	v_cvt_pk_bf16_f32 v73, v73, v74
	v_cvt_pk_bf16_f32 v74, v82, v77
	v_cvt_pk_bf16_f32 v75, v78, v75
	global_store_dwordx4 v[80:81], v[72:75], off sc0 sc1
	v_pk_mul_f32 v[70:71], v[70:71], v[154:155] op_sel_hi:[1,0]
	v_max_f32_e32 v65, 0, v65
	v_mul_f32_e32 v72, v64, v64
	v_max_f32_e32 v64, 0, v69
	v_max_f32_e32 v66, 0, v66
	v_max_f32_e32 v68, 0, v68
	v_mul_f32_e32 v64, v64, v64
	v_mul_f32_e32 v69, v65, v65
	v_max_f32_e32 v65, 0, v70
	v_mul_f32_e32 v70, v66, v66
	v_max_f32_e32 v66, 0, v71
	v_max_f32_e32 v67, 0, v67
	v_mul_f32_e32 v68, v68, v68
	v_mul_f32_e32 v65, v65, v65
	v_mul_f32_e32 v66, v66, v66
	v_mul_f32_e32 v67, v67, v67
	v_cvt_pk_bf16_f32 v64, v68, v64
	v_cvt_pk_bf16_f32 v65, v65, v66
	v_cvt_pk_bf16_f32 v66, v72, v69
	v_cvt_pk_bf16_f32 v67, v70, v67
	global_store_dwordx4 v[80:81], v[64:67], off offset:256 sc0 sc1
	v_pk_mul_f32 v[56:57], v[56:57], v[152:153] op_sel_hi:[1,0]
	v_pk_mul_f32 v[60:61], v[60:61], v[152:153] op_sel_hi:[1,0]
	v_add_u32_e32 v64, 0x80, v138
	v_ashrrev_i32_e32 v67, 31, v64
	v_mad_u64_u32 v[64:65], s[40:41], v64, s67, 0
	v_mov_b32_e32 v66, v65
	v_mad_u64_u32 v[66:67], s[40:41], v67, s67, v[66:67]
	v_pk_mul_f32 v[58:59], v[58:59], v[152:153] op_sel_hi:[1,0]
	v_max_f32_e32 v56, 0, v56
	v_mov_b32_e32 v65, v66
	v_pk_mul_f32 v[62:63], v[62:63], v[152:153] op_sel_hi:[1,0]
	v_mul_f32_e32 v66, v56, v56
	v_max_f32_e32 v56, 0, v61
	v_max_f32_e32 v57, 0, v57
	v_max_f32_e32 v58, 0, v58
	v_lshl_add_u64 v[64:65], v[64:65], 1, s[96:97]
	v_max_f32_e32 v60, 0, v60
	v_mul_f32_e32 v56, v56, v56
	v_mul_f32_e32 v61, v57, v57
	v_max_f32_e32 v57, 0, v62
	v_mul_f32_e32 v62, v58, v58
	v_max_f32_e32 v58, 0, v63
	v_max_f32_e32 v59, 0, v59
	v_pk_mul_f32 v[48:49], v[48:49], v[152:153] op_sel_hi:[1,0]
	v_lshl_add_u64 v[64:65], v[64:65], 0, v[156:157]
	v_mul_f32_e32 v60, v60, v60
	v_mul_f32_e32 v57, v57, v57
	v_mul_f32_e32 v58, v58, v58
	v_mul_f32_e32 v59, v59, v59
	v_cvt_pk_bf16_f32 v56, v60, v56
	v_pk_mul_f32 v[52:53], v[52:53], v[152:153] op_sel_hi:[1,0]
	v_pk_mul_f32 v[50:51], v[50:51], v[152:153] op_sel_hi:[1,0]
	v_max_f32_e32 v48, 0, v48
	v_cvt_pk_bf16_f32 v57, v57, v58
	v_cvt_pk_bf16_f32 v58, v66, v61
	v_cvt_pk_bf16_f32 v59, v62, v59
	global_store_dwordx4 v[64:65], v[56:59], off sc0 sc1
	v_pk_mul_f32 v[54:55], v[54:55], v[152:153] op_sel_hi:[1,0]
	v_max_f32_e32 v49, 0, v49
	v_mul_f32_e32 v56, v48, v48
	v_max_f32_e32 v48, 0, v53
	v_max_f32_e32 v50, 0, v50
	v_max_f32_e32 v52, 0, v52
	v_mul_f32_e32 v48, v48, v48
	v_mul_f32_e32 v53, v49, v49
	v_max_f32_e32 v49, 0, v54
	v_mul_f32_e32 v54, v50, v50
	v_max_f32_e32 v50, 0, v55
	v_max_f32_e32 v51, 0, v51
	v_mul_f32_e32 v52, v52, v52
	v_mul_f32_e32 v49, v49, v49
	v_mul_f32_e32 v50, v50, v50
	v_mul_f32_e32 v51, v51, v51
	v_cvt_pk_bf16_f32 v48, v52, v48
	v_cvt_pk_bf16_f32 v49, v49, v50
	v_cvt_pk_bf16_f32 v50, v56, v53
	v_cvt_pk_bf16_f32 v51, v54, v51
	global_store_dwordx4 v[64:65], v[48:51], off offset:256 sc0 sc1
	v_pk_mul_f32 v[40:41], v[40:41], v[150:151] op_sel_hi:[1,0]
	v_pk_mul_f32 v[44:45], v[44:45], v[150:151] op_sel_hi:[1,0]
	v_add_u32_e32 v48, 0x90, v138
	v_ashrrev_i32_e32 v51, 31, v48
	v_mad_u64_u32 v[48:49], s[40:41], v48, s67, 0
	v_mov_b32_e32 v50, v49
	v_mad_u64_u32 v[50:51], s[40:41], v51, s67, v[50:51]
	v_pk_mul_f32 v[42:43], v[42:43], v[150:151] op_sel_hi:[1,0]
	v_max_f32_e32 v40, 0, v40
	v_mov_b32_e32 v49, v50
	v_pk_mul_f32 v[46:47], v[46:47], v[150:151] op_sel_hi:[1,0]
	v_mul_f32_e32 v50, v40, v40
	v_max_f32_e32 v40, 0, v45
	v_max_f32_e32 v41, 0, v41
	v_max_f32_e32 v42, 0, v42
	v_lshl_add_u64 v[48:49], v[48:49], 1, s[96:97]
	v_max_f32_e32 v44, 0, v44
	v_mul_f32_e32 v40, v40, v40
	v_mul_f32_e32 v45, v41, v41
	v_max_f32_e32 v41, 0, v46
	v_mul_f32_e32 v46, v42, v42
; #define PG8_GAS __attribute__((address_space(1)))
;     __device__ __forceinline__ void operator()(const f32x4 (&acc)[2][2][4][2], const Unit& u, int wr, int wc, int fr, int fq) const {
;     ...
;         for (int ai = 0; ai < 2; ++ai)
; #pragma unroll
;             for (int m = 0; m < 4; ++m) { PG8_GAS bf16_t* rowp = (PG8_GAS bf16_t*)O + (size_t)(row0 + ai * HALF + m * 16) * ldc + col0;
;                 const float rs = rsv[ai][m];
; #pragma unroll
;                 for (int bj = 0; bj < 2; ++bj) { f32x4 v0 = acc[ai][bj][m][0] * rs, v1 = acc[ai][bj][m][1] * rs;
;                     if (mode != 0) {
;                         const bool span = mode == 1 ? ((wc & 1) == 0 && (u.pn % rmod) < rlim) : (((u.pn * 8 + bj * 4 + wc) % 3) == 2);
;                         if (span) {
;                             const int pos = (row0 + ai * HALF + m * 16) & smask;
;                             const PG8_GAS f32x4* t4 = (const PG8_GAS f32x4*)((const PG8_GAS float*)tab + (mode == 1 ? (size_t)pos * 16 : (size_t)pos * 32 + 16 * (fq & 1)));
;                             const int dist = mode == 1 ? 16 : 32; const bool part = mode == 1 ? fq < 2 : true; const bool firsth = mode == 1 ? fq == 0 : fq < 2;
;                             const f32x4 c0 = t4[0], c1 = t4[1], c2 = t4[2], c3 = t4[3];
;                             f32x4 o0, o1;
; #pragma unroll
;                             for (int e = 0; e < 4; ++e) { o0[e] = __shfl_xor(v0[e], dist); o1[e] = __shfl_xor(v1[e], dist); }
;                             if (part) { const float sg = firsth ? -1.0f : 1.0f;
;                                 v0[0] = v0[0] * c0.x + sg * o0[0] * c0.y; v0[1] = v0[1] * c0.z + sg * o0[1] * c0.w; v0[2] = v0[2] * c1.x + sg * o0[2] * c1.y; v0[3] = v0[3] * c1.z + sg * o0[3] * c1.w;
;                                 v1[0] = v1[0] * c2.x + sg * o1[0] * c2.y; v1[1] = v1[1] * c2.z + sg * o1[1] * c2.w; v1[2] = v1[2] * c3.x + sg * o1[2] * c3.y; v1[3] = v1[3] * c3.z + sg * o1[3] * c3.w; }
;                         }
;                     }
;                     if (ACT == 1) {
; #pragma unroll
;                         for (int e = 0; e < 4; ++e) { float a = v0[e] > 0.f ? v0[e] : 0.f; v0[e] = a * a; float b = v1[e] > 0.f ? v1[e] : 0.f; v1[e] = b * b; } }
;                     u32x4 w; w.x = cvt_pk_bf16(v0[0], v0[1]); w.y = cvt_pk_bf16(v0[2], v0[3]); w.z = cvt_pk_bf16(v1[0], v1[1]); w.w = cvt_pk_bf16(v1[2], v1[3]);
	v_max_f32_e32 v42, 0, v47
	v_max_f32_e32 v43, 0, v43
	v_pk_mul_f32 v[32:33], v[32:33], v[150:151] op_sel_hi:[1,0]
	v_lshl_add_u64 v[48:49], v[48:49], 0, v[156:157]
	v_mul_f32_e32 v44, v44, v44
	v_mul_f32_e32 v41, v41, v41
	v_mul_f32_e32 v42, v42, v42
	v_mul_f32_e32 v43, v43, v43
	v_cvt_pk_bf16_f32 v40, v44, v40
	v_pk_mul_f32 v[36:37], v[36:37], v[150:151] op_sel_hi:[1,0]
	v_pk_mul_f32 v[34:35], v[34:35], v[150:151] op_sel_hi:[1,0]
	v_max_f32_e32 v32, 0, v32
	v_cvt_pk_bf16_f32 v41, v41, v42
	v_cvt_pk_bf16_f32 v42, v50, v45
	v_cvt_pk_bf16_f32 v43, v46, v43
	global_store_dwordx4 v[48:49], v[40:43], off sc0 sc1
	v_pk_mul_f32 v[38:39], v[38:39], v[150:151] op_sel_hi:[1,0]
	v_max_f32_e32 v33, 0, v33
	v_mul_f32_e32 v40, v32, v32
	v_max_f32_e32 v32, 0, v37
	v_max_f32_e32 v34, 0, v34
	v_max_f32_e32 v36, 0, v36
	v_mul_f32_e32 v32, v32, v32
	v_mul_f32_e32 v37, v33, v33
	v_max_f32_e32 v33, 0, v38
	v_mul_f32_e32 v38, v34, v34
	v_max_f32_e32 v34, 0, v39
	v_max_f32_e32 v35, 0, v35
	v_mul_f32_e32 v36, v36, v36
	v_mul_f32_e32 v33, v33, v33
	v_mul_f32_e32 v34, v34, v34
	v_mul_f32_e32 v35, v35, v35
	v_cvt_pk_bf16_f32 v32, v36, v32
	v_cvt_pk_bf16_f32 v33, v33, v34
	v_cvt_pk_bf16_f32 v34, v40, v37
	v_cvt_pk_bf16_f32 v35, v38, v35
	global_store_dwordx4 v[48:49], v[32:35], off offset:256 sc0 sc1
	v_pk_mul_f32 v[24:25], v[24:25], v[148:149] op_sel_hi:[1,0]
	v_pk_mul_f32 v[28:29], v[28:29], v[148:149] op_sel_hi:[1,0]
	v_add_u32_e32 v32, 0xa0, v138
	v_ashrrev_i32_e32 v35, 31, v32
	v_mad_u64_u32 v[32:33], s[40:41], v32, s67, 0
	v_mov_b32_e32 v34, v33
	v_mad_u64_u32 v[34:35], s[40:41], v35, s67, v[34:35]
	v_pk_mul_f32 v[26:27], v[26:27], v[148:149] op_sel_hi:[1,0]
	v_max_f32_e32 v24, 0, v24
	v_mov_b32_e32 v33, v34
	v_pk_mul_f32 v[30:31], v[30:31], v[148:149] op_sel_hi:[1,0]
	v_mul_f32_e32 v34, v24, v24
	v_max_f32_e32 v24, 0, v29
	v_max_f32_e32 v25, 0, v25
	v_max_f32_e32 v26, 0, v26
	v_lshl_add_u64 v[32:33], v[32:33], 1, s[96:97]
	v_max_f32_e32 v28, 0, v28
	v_mul_f32_e32 v24, v24, v24
	v_mul_f32_e32 v29, v25, v25
	v_max_f32_e32 v25, 0, v30
	v_mul_f32_e32 v30, v26, v26
	v_max_f32_e32 v26, 0, v31
	v_max_f32_e32 v27, 0, v27
	v_pk_mul_f32 v[16:17], v[16:17], v[148:149] op_sel_hi:[1,0]
	v_lshl_add_u64 v[32:33], v[32:33], 0, v[156:157]
	v_mul_f32_e32 v28, v28, v28
	v_mul_f32_e32 v25, v25, v25
	v_mul_f32_e32 v26, v26, v26
	v_mul_f32_e32 v27, v27, v27
	v_cvt_pk_bf16_f32 v24, v28, v24
	v_pk_mul_f32 v[20:21], v[20:21], v[148:149] op_sel_hi:[1,0]
	v_pk_mul_f32 v[18:19], v[18:19], v[148:149] op_sel_hi:[1,0]
	v_max_f32_e32 v16, 0, v16
	v_cvt_pk_bf16_f32 v25, v25, v26
	v_cvt_pk_bf16_f32 v26, v34, v29
	v_cvt_pk_bf16_f32 v27, v30, v27
	global_store_dwordx4 v[32:33], v[24:27], off sc0 sc1
	v_pk_mul_f32 v[22:23], v[22:23], v[148:149] op_sel_hi:[1,0]
	v_max_f32_e32 v17, 0, v17
	v_mul_f32_e32 v24, v16, v16
	v_max_f32_e32 v16, 0, v21
	v_max_f32_e32 v18, 0, v18
	v_max_f32_e32 v20, 0, v20
	v_mul_f32_e32 v16, v16, v16
	v_mul_f32_e32 v21, v17, v17
	v_max_f32_e32 v17, 0, v22
	v_mul_f32_e32 v22, v18, v18
	v_max_f32_e32 v18, 0, v23
	v_max_f32_e32 v19, 0, v19
	v_mul_f32_e32 v20, v20, v20
	v_mul_f32_e32 v17, v17, v17
	v_mul_f32_e32 v18, v18, v18
	v_mul_f32_e32 v19, v19, v19
	v_cvt_pk_bf16_f32 v16, v20, v16
	v_cvt_pk_bf16_f32 v17, v17, v18
	v_cvt_pk_bf16_f32 v18, v24, v21
	v_cvt_pk_bf16_f32 v19, v22, v19
	global_store_dwordx4 v[32:33], v[16:19], off offset:256 sc0 sc1
	v_pk_mul_f32 v[8:9], v[8:9], v[144:145] op_sel_hi:[1,0]
	v_pk_mul_f32 v[12:13], v[12:13], v[144:145] op_sel_hi:[1,0]
	v_add_u32_e32 v16, 0xb0, v138
	v_ashrrev_i32_e32 v19, 31, v16
	v_mad_u64_u32 v[16:17], s[40:41], v16, s67, 0
	v_mov_b32_e32 v18, v17
	v_mad_u64_u32 v[18:19], s[40:41], v19, s67, v[18:19]
	v_pk_mul_f32 v[10:11], v[10:11], v[144:145] op_sel_hi:[1,0]
	v_max_f32_e32 v8, 0, v8
	v_mov_b32_e32 v17, v18
	v_pk_mul_f32 v[14:15], v[14:15], v[144:145] op_sel_hi:[1,0]
	v_mul_f32_e32 v18, v8, v8
	v_max_f32_e32 v8, 0, v13
	v_max_f32_e32 v9, 0, v9
	v_max_f32_e32 v10, 0, v10
	v_lshl_add_u64 v[16:17], v[16:17], 1, s[96:97]
	v_max_f32_e32 v12, 0, v12
	v_mul_f32_e32 v8, v8, v8
	v_mul_f32_e32 v13, v9, v9
	v_max_f32_e32 v9, 0, v14
	v_mul_f32_e32 v14, v10, v10
	v_max_f32_e32 v10, 0, v15
	v_max_f32_e32 v11, 0, v11
	v_pk_mul_f32 v[2:3], v[2:3], v[144:145] op_sel_hi:[1,0]
	v_pk_mul_f32 v[0:1], v[0:1], v[144:145] op_sel_hi:[1,0]
	v_lshl_add_u64 v[16:17], v[16:17], 0, v[156:157]
	v_mul_f32_e32 v12, v12, v12
	v_mul_f32_e32 v9, v9, v9
	v_mul_f32_e32 v10, v10, v10
	v_mul_f32_e32 v11, v11, v11
	v_cvt_pk_bf16_f32 v8, v12, v8
	v_pk_mul_f32 v[6:7], v[6:7], v[144:145] op_sel_hi:[1,0]
	v_pk_mul_f32 v[4:5], v[4:5], v[144:145] op_sel_hi:[1,0]
	v_max_f32_e32 v0, 0, v0
	v_max_f32_e32 v1, 0, v1
	v_max_f32_e32 v2, 0, v2
	v_cvt_pk_bf16_f32 v9, v9, v10
	v_cvt_pk_bf16_f32 v10, v18, v13
	v_cvt_pk_bf16_f32 v11, v14, v11
	global_store_dwordx4 v[16:17], v[8:11], off sc0 sc1
	v_max_f32_e32 v3, 0, v3
	v_max_f32_e32 v4, 0, v4
	v_mul_f32_e32 v8, v0, v0
	v_max_f32_e32 v0, 0, v5
	v_mul_f32_e32 v5, v1, v1
	v_max_f32_e32 v1, 0, v6
	v_mul_f32_e32 v6, v2, v2
	v_max_f32_e32 v2, 0, v7
	v_mul_f32_e32 v0, v0, v0
	v_mul_f32_e32 v1, v1, v1
	v_mul_f32_e32 v2, v2, v2
	v_mul_f32_e32 v3, v3, v3
	s_and_b64 vcc, exec, s[0:1]
	s_mov_b64 s[0:1], -1
	v_mul_f32_e32 v4, v4, v4
	v_cvt_pk_bf16_f32 v0, v4, v0
	v_cvt_pk_bf16_f32 v1, v1, v2
	v_cvt_pk_bf16_f32 v2, v8, v5
	v_cvt_pk_bf16_f32 v3, v6, v3
	global_store_dwordx4 v[16:17], v[0:3], off offset:256 sc0 sc1
	s_cbranch_vccnz .LBB0_414
	s_andn2_b64 vcc, exec, s[22:23]
	s_cbranch_vccnz .LBB0_413
	s_barrier
	s_branch .LBB0_413

;     __device__ __forceinline__ void operator()(const f32x4 (&acc)[2][2][4][2], const Unit& u, int wr, int wc, int fr, int fq) const {
;     ...
;             for (int m = 0; m < 4; ++m) { PG8_GAS bf16_t* rowp = (PG8_GAS bf16_t*)O + (size_t)(row0 + ai * HALF + m * 16) * ldc + col0;
;                 const float rs = rsv[ai][m];
; #pragma unroll
;                 for (int bj = 0; bj < 2; ++bj) { f32x4 v0 = acc[ai][bj][m][0] * rs, v1 = acc[ai][bj][m][1] * rs;
;                     if (mode != 0) {
;                         const bool span = mode == 1 ? ((wc & 1) == 0 && (u.pn % rmod) < rlim) : (((u.pn * 8 + bj * 4 + wc) % 3) == 2);
;                         if (span) {
;                             const int pos = (row0 + ai * HALF + m * 16) & smask;
;                             const PG8_GAS f32x4* t4 = (const PG8_GAS f32x4*)((const PG8_GAS float*)tab + (mode == 1 ? (size_t)pos * 16 : (size_t)pos * 32 + 16 * (fq & 1)));
;                             const int dist = mode == 1 ? 16 : 32; const bool part = mode == 1 ? fq < 2 : true; const bool firsth = mode == 1 ? fq == 0 : fq < 2;
;                             const f32x4 c0 = t4[0], c1 = t4[1], c2 = t4[2], c3 = t4[3];
;                             f32x4 o0, o1;
; #pragma unroll
;                             for (int e = 0; e < 4; ++e) { o0[e] = __shfl_xor(v0[e], dist); o1[e] = __shfl_xor(v1[e], dist); }
;                             if (part) { const float sg = firsth ? -1.0f : 1.0f;
;                                 v0[0] = v0[0] * c0.x + sg * o0[0] * c0.y; v0[1] = v0[1] * c0.z + sg * o0[1] * c0.w; v0[2] = v0[2] * c1.x + sg * o0[2] * c1.y; v0[3] = v0[3] * c1.z + sg * o0[3] * c1.w;
;                                 v1[0] = v1[0] * c2.x + sg * o1[0] * c2.y; v1[1] = v1[1] * c2.z + sg * o1[1] * c2.w; v1[2] = v1[2] * c3.x + sg * o1[2] * c3.y; v1[3] = v1[3] * c3.z + sg * o1[3] * c3.w; }
;                         }
;                     }
;                     if (ACT == 1) {
; #pragma unroll
;                         for (int e = 0; e < 4; ++e) { float a = v0[e] > 0.f ? v0[e] : 0.f; v0[e] = a * a; float b = v1[e] > 0.f ? v1[e] : 0.f; v1[e] = b * b; } }
;                     u32x4 w; w.x = cvt_pk_bf16(v0[0], v0[1]); w.y = cvt_pk_bf16(v0[2], v0[3]); w.z = cvt_pk_bf16(v1[0], v1[1]); w.w = cvt_pk_bf16(v1[2], v1[3]);
;                     *(PG8_GAS u32x4*)(rowp + bj * HALF) = w; } }
.LBB0_477:
	s_waitcnt lgkmcnt(0)
	v_mad_u64_u32 v[122:123], s[40:41], v142, s67, 0
	v_mov_b32_e32 v168, v123
	v_mad_u64_u32 v[168:169], s[40:41], v143, s67, v[168:169]
	v_lshl_or_b32 v120, s26, 8, v166
	v_mov_b32_e32 v123, v168
	v_ashrrev_i32_e32 v121, 31, v120
	v_lshl_add_u64 v[122:123], v[122:123], 1, s[96:97]
	v_lshl_add_u64 v[122:123], v[120:121], 1, v[122:123]
	v_cvt_pk_bf16_f32 v124, v124, v125
	v_cvt_pk_bf16_f32 v125, v126, v127
	v_cvt_pk_bf16_f32 v126, v160, v161
	v_cvt_pk_bf16_f32 v127, v162, v163
	global_store_dwordx4 v[122:123], v[124:127], off sc0 sc1
	v_mov_b32_e32 v159, v158
	v_pk_mul_f32 v[116:117], v[116:117], v[158:159]
	v_mov_b32_e32 v124, v158
	v_mov_b32_e32 v125, v158
	v_pk_mul_f32 v[118:119], v[118:119], v[124:125]
	v_pk_mul_f32 v[114:115], v[114:115], v[124:125]
	s_cmp_lt_i32 s66, 1
	v_pk_mul_f32 v[112:113], v[112:113], v[158:159]
	s_cbranch_scc1 .LBB0_488
	s_cmp_lg_u32 s66, 1
	s_cbranch_scc0 .LBB0_480
	s_lshl_b32 s35, s26, 3
	s_or_b32 s35, s35, s12
	s_mul_hi_i32 s40, s35, 0x55555556
	s_lshr_b32 s41, s40, 31
	s_add_i32 s40, s40, s41
	s_mul_i32 s40, s40, 3
	s_sub_i32 s35, s35, s40
	s_cmp_eq_u32 s35, 2
	s_mov_b64 s[40:41], -1
	s_cselect_b64 s[44:45], -1, 0
	s_cbranch_execz .LBB0_481
	s_branch .LBB0_483

;     __device__ __forceinline__ void operator()(const f32x4 (&acc)[2][2][4][2], const Unit& u, int wr, int wc, int fr, int fq) const {
;     ...
;             for (int m = 0; m < 4; ++m) { PG8_GAS bf16_t* rowp = (PG8_GAS bf16_t*)O + (size_t)(row0 + ai * HALF + m * 16) * ldc + col0;
;                 const float rs = rsv[ai][m];
; #pragma unroll
;                 for (int bj = 0; bj < 2; ++bj) { f32x4 v0 = acc[ai][bj][m][0] * rs, v1 = acc[ai][bj][m][1] * rs;
;                     if (mode != 0) {
;                         const bool span = mode == 1 ? ((wc & 1) == 0 && (u.pn % rmod) < rlim) : (((u.pn * 8 + bj * 4 + wc) % 3) == 2);
;                         if (span) {
;                             const int pos = (row0 + ai * HALF + m * 16) & smask;
;                             const PG8_GAS f32x4* t4 = (const PG8_GAS f32x4*)((const PG8_GAS float*)tab + (mode == 1 ? (size_t)pos * 16 : (size_t)pos * 32 + 16 * (fq & 1)));
;                             const int dist = mode == 1 ? 16 : 32; const bool part = mode == 1 ? fq < 2 : true; const bool firsth = mode == 1 ? fq == 0 : fq < 2;
;                             const f32x4 c0 = t4[0], c1 = t4[1], c2 = t4[2], c3 = t4[3];
;                             f32x4 o0, o1;
; #pragma unroll
;                             for (int e = 0; e < 4; ++e) { o0[e] = __shfl_xor(v0[e], dist); o1[e] = __shfl_xor(v1[e], dist); }
;                             if (part) { const float sg = firsth ? -1.0f : 1.0f;
;                                 v0[0] = v0[0] * c0.x + sg * o0[0] * c0.y; v0[1] = v0[1] * c0.z + sg * o0[1] * c0.w; v0[2] = v0[2] * c1.x + sg * o0[2] * c1.y; v0[3] = v0[3] * c1.z + sg * o0[3] * c1.w;
;                                 v1[0] = v1[0] * c2.x + sg * o1[0] * c2.y; v1[1] = v1[1] * c2.z + sg * o1[1] * c2.w; v1[2] = v1[2] * c3.x + sg * o1[2] * c3.y; v1[3] = v1[3] * c3.z + sg * o1[3] * c3.w; }
;                         }
;                     }
;                     if (ACT == 1) {
; #pragma unroll
;                         for (int e = 0; e < 4; ++e) { float a = v0[e] > 0.f ? v0[e] : 0.f; v0[e] = a * a; float b = v1[e] > 0.f ? v1[e] : 0.f; v1[e] = b * b; } }
;                     u32x4 w; w.x = cvt_pk_bf16(v0[0], v0[1]); w.y = cvt_pk_bf16(v0[2], v0[3]); w.z = cvt_pk_bf16(v1[0], v1[1]); w.w = cvt_pk_bf16(v1[2], v1[3]);
;                     *(PG8_GAS u32x4*)(rowp + bj * HALF) = w; } }
.LBB0_488:
	v_cvt_pk_bf16_f32 v116, v116, v117
	v_cvt_pk_bf16_f32 v117, v118, v119
	v_cvt_pk_bf16_f32 v118, v112, v113
	v_cvt_pk_bf16_f32 v119, v114, v115
	global_store_dwordx4 v[122:123], v[116:119], off offset:256 sc0 sc1
	v_pk_mul_f32 v[110:111], v[110:111], v[156:157] op_sel_hi:[1,0]
	v_pk_mul_f32 v[108:109], v[108:109], v[156:157] op_sel_hi:[1,0]
	v_or_b32_e32 v116, 16, v142
	v_pk_mul_f32 v[112:113], v[106:107], v[156:157] op_sel_hi:[1,0]
	s_cmp_lt_i32 s66, 1
	v_pk_mul_f32 v[106:107], v[104:105], v[156:157] op_sel_hi:[1,0]
	s_cbranch_scc1 .LBB0_499
	s_cmp_lg_u32 s66, 1
	s_cbranch_scc0 .LBB0_491
	s_lshl_b32 s35, s26, 3
	s_or_b32 s35, s35, s50
	s_mul_hi_i32 s40, s35, 0x55555556
	s_lshr_b32 s41, s40, 31
	s_add_i32 s40, s40, s41
	s_mul_i32 s40, s40, 3
	s_sub_i32 s35, s35, s40
	s_cmp_eq_u32 s35, 2
	s_mov_b64 s[40:41], -1
	s_cselect_b64 s[44:45], -1, 0
	s_cbranch_execz .LBB0_492
	s_branch .LBB0_494

;     __device__ __forceinline__ void operator()(const f32x4 (&acc)[2][2][4][2], const Unit& u, int wr, int wc, int fr, int fq) const {
;     ...
;             for (int m = 0; m < 4; ++m) { PG8_GAS bf16_t* rowp = (PG8_GAS bf16_t*)O + (size_t)(row0 + ai * HALF + m * 16) * ldc + col0;
;                 const float rs = rsv[ai][m];
; #pragma unroll
;                 for (int bj = 0; bj < 2; ++bj) { f32x4 v0 = acc[ai][bj][m][0] * rs, v1 = acc[ai][bj][m][1] * rs;
;                     if (mode != 0) {
;                         const bool span = mode == 1 ? ((wc & 1) == 0 && (u.pn % rmod) < rlim) : (((u.pn * 8 + bj * 4 + wc) % 3) == 2);
;                         if (span) {
;                             const int pos = (row0 + ai * HALF + m * 16) & smask;
;                             const PG8_GAS f32x4* t4 = (const PG8_GAS f32x4*)((const PG8_GAS float*)tab + (mode == 1 ? (size_t)pos * 16 : (size_t)pos * 32 + 16 * (fq & 1)));
;                             const int dist = mode == 1 ? 16 : 32; const bool part = mode == 1 ? fq < 2 : true; const bool firsth = mode == 1 ? fq == 0 : fq < 2;
;                             const f32x4 c0 = t4[0], c1 = t4[1], c2 = t4[2], c3 = t4[3];
;                             f32x4 o0, o1;
; #pragma unroll
;                             for (int e = 0; e < 4; ++e) { o0[e] = __shfl_xor(v0[e], dist); o1[e] = __shfl_xor(v1[e], dist); }
;                             if (part) { const float sg = firsth ? -1.0f : 1.0f;
;                                 v0[0] = v0[0] * c0.x + sg * o0[0] * c0.y; v0[1] = v0[1] * c0.z + sg * o0[1] * c0.w; v0[2] = v0[2] * c1.x + sg * o0[2] * c1.y; v0[3] = v0[3] * c1.z + sg * o0[3] * c1.w;
;                                 v1[0] = v1[0] * c2.x + sg * o1[0] * c2.y; v1[1] = v1[1] * c2.z + sg * o1[1] * c2.w; v1[2] = v1[2] * c3.x + sg * o1[2] * c3.y; v1[3] = v1[3] * c3.z + sg * o1[3] * c3.w; }
;                         }
;                     }
;                     if (ACT == 1) {
; #pragma unroll
;                         for (int e = 0; e < 4; ++e) { float a = v0[e] > 0.f ? v0[e] : 0.f; v0[e] = a * a; float b = v1[e] > 0.f ? v1[e] : 0.f; v1[e] = b * b; } }
;                     u32x4 w; w.x = cvt_pk_bf16(v0[0], v0[1]); w.y = cvt_pk_bf16(v0[2], v0[3]); w.z = cvt_pk_bf16(v1[0], v1[1]); w.w = cvt_pk_bf16(v1[2], v1[3]);
;                     *(PG8_GAS u32x4*)(rowp + bj * HALF) = w; } }
.LBB0_499:
	s_waitcnt lgkmcnt(0)
	v_mad_u64_u32 v[104:105], s[40:41], v116, s67, 0
	v_ashrrev_i32_e32 v115, 31, v116
	v_mov_b32_e32 v114, v105
	v_mad_u64_u32 v[114:115], s[40:41], v115, s67, v[114:115]
	v_mov_b32_e32 v105, v114
	v_lshl_add_u64 v[104:105], v[104:105], 1, s[96:97]
	v_cvt_pk_bf16_f32 v108, v108, v109
	v_cvt_pk_bf16_f32 v109, v110, v111
	v_cvt_pk_bf16_f32 v110, v106, v107
	v_mov_b32_e32 v157, v156
	v_mov_b32_e32 v106, v156
	v_mov_b32_e32 v107, v156
	v_lshl_add_u64 v[104:105], v[120:121], 1, v[104:105]
	v_pk_mul_f32 v[102:103], v[102:103], v[106:107]
	v_pk_mul_f32 v[100:101], v[100:101], v[156:157]
	v_pk_mul_f32 v[98:99], v[98:99], v[106:107]
	s_cmp_lt_i32 s66, 1
	v_pk_mul_f32 v[96:97], v[96:97], v[156:157]
	v_cvt_pk_bf16_f32 v111, v112, v113
	global_store_dwordx4 v[104:105], v[108:111], off sc0 sc1
	s_cbranch_scc1 .LBB0_510
	s_cmp_lg_u32 s66, 1
	s_cbranch_scc0 .LBB0_502
	s_lshl_b32 s35, s26, 3
	s_or_b32 s35, s35, s12
	s_mul_hi_i32 s40, s35, 0x55555556
	s_lshr_b32 s41, s40, 31
	s_add_i32 s40, s40, s41
	s_mul_i32 s40, s40, 3
	s_sub_i32 s35, s35, s40
	s_cmp_eq_u32 s35, 2
	s_mov_b64 s[40:41], -1
	s_cselect_b64 s[44:45], -1, 0
	s_cbranch_execz .LBB0_503
	s_branch .LBB0_505

;     __device__ __forceinline__ void operator()(const f32x4 (&acc)[2][2][4][2], const Unit& u, int wr, int wc, int fr, int fq) const {
;     ...
;             for (int m = 0; m < 4; ++m) { PG8_GAS bf16_t* rowp = (PG8_GAS bf16_t*)O + (size_t)(row0 + ai * HALF + m * 16) * ldc + col0;
;                 const float rs = rsv[ai][m];
; #pragma unroll
;                 for (int bj = 0; bj < 2; ++bj) { f32x4 v0 = acc[ai][bj][m][0] * rs, v1 = acc[ai][bj][m][1] * rs;
;                     if (mode != 0) {
;                         const bool span = mode == 1 ? ((wc & 1) == 0 && (u.pn % rmod) < rlim) : (((u.pn * 8 + bj * 4 + wc) % 3) == 2);
;                         if (span) {
;                             const int pos = (row0 + ai * HALF + m * 16) & smask;
;                             const PG8_GAS f32x4* t4 = (const PG8_GAS f32x4*)((const PG8_GAS float*)tab + (mode == 1 ? (size_t)pos * 16 : (size_t)pos * 32 + 16 * (fq & 1)));
;                             const int dist = mode == 1 ? 16 : 32; const bool part = mode == 1 ? fq < 2 : true; const bool firsth = mode == 1 ? fq == 0 : fq < 2;
;                             const f32x4 c0 = t4[0], c1 = t4[1], c2 = t4[2], c3 = t4[3];
;                             f32x4 o0, o1;
; #pragma unroll
;                             for (int e = 0; e < 4; ++e) { o0[e] = __shfl_xor(v0[e], dist); o1[e] = __shfl_xor(v1[e], dist); }
;                             if (part) { const float sg = firsth ? -1.0f : 1.0f;
;                                 v0[0] = v0[0] * c0.x + sg * o0[0] * c0.y; v0[1] = v0[1] * c0.z + sg * o0[1] * c0.w; v0[2] = v0[2] * c1.x + sg * o0[2] * c1.y; v0[3] = v0[3] * c1.z + sg * o0[3] * c1.w;
;                                 v1[0] = v1[0] * c2.x + sg * o1[0] * c2.y; v1[1] = v1[1] * c2.z + sg * o1[1] * c2.w; v1[2] = v1[2] * c3.x + sg * o1[2] * c3.y; v1[3] = v1[3] * c3.z + sg * o1[3] * c3.w; }
;                         }
;                     }
;                     if (ACT == 1) {
; #pragma unroll
;                         for (int e = 0; e < 4; ++e) { float a = v0[e] > 0.f ? v0[e] : 0.f; v0[e] = a * a; float b = v1[e] > 0.f ? v1[e] : 0.f; v1[e] = b * b; } }
;                     u32x4 w; w.x = cvt_pk_bf16(v0[0], v0[1]); w.y = cvt_pk_bf16(v0[2], v0[3]); w.z = cvt_pk_bf16(v1[0], v1[1]); w.w = cvt_pk_bf16(v1[2], v1[3]);
;                     *(PG8_GAS u32x4*)(rowp + bj * HALF) = w; } }
.LBB0_510:
	v_cvt_pk_bf16_f32 v100, v100, v101
	v_cvt_pk_bf16_f32 v101, v102, v103
	v_cvt_pk_bf16_f32 v102, v96, v97
	v_cvt_pk_bf16_f32 v103, v98, v99
	global_store_dwordx4 v[104:105], v[100:103], off offset:256 sc0 sc1
	v_pk_mul_f32 v[94:95], v[94:95], v[154:155] op_sel_hi:[1,0]
	v_pk_mul_f32 v[92:93], v[92:93], v[154:155] op_sel_hi:[1,0]
	v_or_b32_e32 v100, 32, v142
	v_pk_mul_f32 v[96:97], v[90:91], v[154:155] op_sel_hi:[1,0]
	s_cmp_lt_i32 s66, 1
	v_pk_mul_f32 v[90:91], v[88:89], v[154:155] op_sel_hi:[1,0]
	s_cbranch_scc1 .LBB0_521
	s_cmp_lg_u32 s66, 1
	s_cbranch_scc0 .LBB0_513
	s_lshl_b32 s35, s26, 3
	s_or_b32 s35, s35, s50
	s_mul_hi_i32 s40, s35, 0x55555556
	s_lshr_b32 s41, s40, 31
	s_add_i32 s40, s40, s41
	s_mul_i32 s40, s40, 3
	s_sub_i32 s35, s35, s40
	s_cmp_eq_u32 s35, 2
	s_mov_b64 s[40:41], -1
	s_cselect_b64 s[44:45], -1, 0
	s_cbranch_execz .LBB0_514
	s_branch .LBB0_516

;     __device__ __forceinline__ void operator()(const f32x4 (&acc)[2][2][4][2], const Unit& u, int wr, int wc, int fr, int fq) const {
;     ...
;             for (int m = 0; m < 4; ++m) { PG8_GAS bf16_t* rowp = (PG8_GAS bf16_t*)O + (size_t)(row0 + ai * HALF + m * 16) * ldc + col0;
;                 const float rs = rsv[ai][m];
; #pragma unroll
;                 for (int bj = 0; bj < 2; ++bj) { f32x4 v0 = acc[ai][bj][m][0] * rs, v1 = acc[ai][bj][m][1] * rs;
;                     if (mode != 0) {
;                         const bool span = mode == 1 ? ((wc & 1) == 0 && (u.pn % rmod) < rlim) : (((u.pn * 8 + bj * 4 + wc) % 3) == 2);
;                         if (span) {
;                             const int pos = (row0 + ai * HALF + m * 16) & smask;
;                             const PG8_GAS f32x4* t4 = (const PG8_GAS f32x4*)((const PG8_GAS float*)tab + (mode == 1 ? (size_t)pos * 16 : (size_t)pos * 32 + 16 * (fq & 1)));
;                             const int dist = mode == 1 ? 16 : 32; const bool part = mode == 1 ? fq < 2 : true; const bool firsth = mode == 1 ? fq == 0 : fq < 2;
;                             const f32x4 c0 = t4[0], c1 = t4[1], c2 = t4[2], c3 = t4[3];
;                             f32x4 o0, o1;
; #pragma unroll
;                             for (int e = 0; e < 4; ++e) { o0[e] = __shfl_xor(v0[e], dist); o1[e] = __shfl_xor(v1[e], dist); }
;                             if (part) { const float sg = firsth ? -1.0f : 1.0f;
;                                 v0[0] = v0[0] * c0.x + sg * o0[0] * c0.y; v0[1] = v0[1] * c0.z + sg * o0[1] * c0.w; v0[2] = v0[2] * c1.x + sg * o0[2] * c1.y; v0[3] = v0[3] * c1.z + sg * o0[3] * c1.w;
;                                 v1[0] = v1[0] * c2.x + sg * o1[0] * c2.y; v1[1] = v1[1] * c2.z + sg * o1[1] * c2.w; v1[2] = v1[2] * c3.x + sg * o1[2] * c3.y; v1[3] = v1[3] * c3.z + sg * o1[3] * c3.w; }
;                         }
;                     }
;                     if (ACT == 1) {
; #pragma unroll
;                         for (int e = 0; e < 4; ++e) { float a = v0[e] > 0.f ? v0[e] : 0.f; v0[e] = a * a; float b = v1[e] > 0.f ? v1[e] : 0.f; v1[e] = b * b; } }
;                     u32x4 w; w.x = cvt_pk_bf16(v0[0], v0[1]); w.y = cvt_pk_bf16(v0[2], v0[3]); w.z = cvt_pk_bf16(v1[0], v1[1]); w.w = cvt_pk_bf16(v1[2], v1[3]);
;                     *(PG8_GAS u32x4*)(rowp + bj * HALF) = w; } }
.LBB0_521:
	s_waitcnt lgkmcnt(0)
	v_mad_u64_u32 v[88:89], s[40:41], v100, s67, 0
	v_ashrrev_i32_e32 v99, 31, v100
	v_mov_b32_e32 v98, v89
	v_mad_u64_u32 v[98:99], s[40:41], v99, s67, v[98:99]
	v_mov_b32_e32 v89, v98
	v_lshl_add_u64 v[88:89], v[88:89], 1, s[96:97]
	v_cvt_pk_bf16_f32 v92, v92, v93
	v_cvt_pk_bf16_f32 v93, v94, v95
	v_cvt_pk_bf16_f32 v94, v90, v91
	v_mov_b32_e32 v155, v154
	v_mov_b32_e32 v90, v154
	v_mov_b32_e32 v91, v154
	v_lshl_add_u64 v[88:89], v[120:121], 1, v[88:89]
	v_pk_mul_f32 v[86:87], v[86:87], v[90:91]
	v_pk_mul_f32 v[84:85], v[84:85], v[154:155]
	v_pk_mul_f32 v[82:83], v[82:83], v[90:91]
	s_cmp_lt_i32 s66, 1
	v_pk_mul_f32 v[80:81], v[80:81], v[154:155]
	v_cvt_pk_bf16_f32 v95, v96, v97
	global_store_dwordx4 v[88:89], v[92:95], off sc0 sc1
	s_cbranch_scc1 .LBB0_532
	s_cmp_lg_u32 s66, 1
	s_cbranch_scc0 .LBB0_524
	s_lshl_b32 s35, s26, 3
	s_or_b32 s35, s35, s12
	s_mul_hi_i32 s40, s35, 0x55555556
	s_lshr_b32 s41, s40, 31
	s_add_i32 s40, s40, s41
	s_mul_i32 s40, s40, 3
	s_sub_i32 s35, s35, s40
	s_cmp_eq_u32 s35, 2
	s_mov_b64 s[40:41], -1
	s_cselect_b64 s[44:45], -1, 0
	s_cbranch_execz .LBB0_525
	s_branch .LBB0_527

;     __device__ __forceinline__ void operator()(const f32x4 (&acc)[2][2][4][2], const Unit& u, int wr, int wc, int fr, int fq) const {
;     ...
;             for (int m = 0; m < 4; ++m) { PG8_GAS bf16_t* rowp = (PG8_GAS bf16_t*)O + (size_t)(row0 + ai * HALF + m * 16) * ldc + col0;
;                 const float rs = rsv[ai][m];
; #pragma unroll
;                 for (int bj = 0; bj < 2; ++bj) { f32x4 v0 = acc[ai][bj][m][0] * rs, v1 = acc[ai][bj][m][1] * rs;
;                     if (mode != 0) {
;                         const bool span = mode == 1 ? ((wc & 1) == 0 && (u.pn % rmod) < rlim) : (((u.pn * 8 + bj * 4 + wc) % 3) == 2);
;                         if (span) {
;                             const int pos = (row0 + ai * HALF + m * 16) & smask;
;                             const PG8_GAS f32x4* t4 = (const PG8_GAS f32x4*)((const PG8_GAS float*)tab + (mode == 1 ? (size_t)pos * 16 : (size_t)pos * 32 + 16 * (fq & 1)));
;                             const int dist = mode == 1 ? 16 : 32; const bool part = mode == 1 ? fq < 2 : true; const bool firsth = mode == 1 ? fq == 0 : fq < 2;
;                             const f32x4 c0 = t4[0], c1 = t4[1], c2 = t4[2], c3 = t4[3];
;                             f32x4 o0, o1;
; #pragma unroll
;                             for (int e = 0; e < 4; ++e) { o0[e] = __shfl_xor(v0[e], dist); o1[e] = __shfl_xor(v1[e], dist); }
;                             if (part) { const float sg = firsth ? -1.0f : 1.0f;
;                                 v0[0] = v0[0] * c0.x + sg * o0[0] * c0.y; v0[1] = v0[1] * c0.z + sg * o0[1] * c0.w; v0[2] = v0[2] * c1.x + sg * o0[2] * c1.y; v0[3] = v0[3] * c1.z + sg * o0[3] * c1.w;
;                                 v1[0] = v1[0] * c2.x + sg * o1[0] * c2.y; v1[1] = v1[1] * c2.z + sg * o1[1] * c2.w; v1[2] = v1[2] * c3.x + sg * o1[2] * c3.y; v1[3] = v1[3] * c3.z + sg * o1[3] * c3.w; }
;                         }
;                     }
;                     if (ACT == 1) {
; #pragma unroll
;                         for (int e = 0; e < 4; ++e) { float a = v0[e] > 0.f ? v0[e] : 0.f; v0[e] = a * a; float b = v1[e] > 0.f ? v1[e] : 0.f; v1[e] = b * b; } }
;                     u32x4 w; w.x = cvt_pk_bf16(v0[0], v0[1]); w.y = cvt_pk_bf16(v0[2], v0[3]); w.z = cvt_pk_bf16(v1[0], v1[1]); w.w = cvt_pk_bf16(v1[2], v1[3]);
;                     *(PG8_GAS u32x4*)(rowp + bj * HALF) = w; } }
.LBB0_532:
	v_cvt_pk_bf16_f32 v84, v84, v85
	v_cvt_pk_bf16_f32 v85, v86, v87
	v_cvt_pk_bf16_f32 v86, v80, v81
	v_cvt_pk_bf16_f32 v87, v82, v83
	global_store_dwordx4 v[88:89], v[84:87], off offset:256 sc0 sc1
	v_pk_mul_f32 v[78:79], v[78:79], v[152:153] op_sel_hi:[1,0]
	v_pk_mul_f32 v[76:77], v[76:77], v[152:153] op_sel_hi:[1,0]
	v_or_b32_e32 v84, 48, v142
	v_pk_mul_f32 v[80:81], v[74:75], v[152:153] op_sel_hi:[1,0]
	s_cmp_lt_i32 s66, 1
	v_pk_mul_f32 v[74:75], v[72:73], v[152:153] op_sel_hi:[1,0]
	s_cbranch_scc1 .LBB0_543
	s_cmp_lg_u32 s66, 1
	s_cbranch_scc0 .LBB0_535
	s_lshl_b32 s35, s26, 3
	s_or_b32 s35, s35, s50
	s_mul_hi_i32 s40, s35, 0x55555556
	s_lshr_b32 s41, s40, 31
	s_add_i32 s40, s40, s41
	s_mul_i32 s40, s40, 3
	s_sub_i32 s35, s35, s40
	s_cmp_eq_u32 s35, 2
	s_mov_b64 s[40:41], -1
	s_cselect_b64 s[44:45], -1, 0
	s_cbranch_execz .LBB0_536
	s_branch .LBB0_538

;     __device__ __forceinline__ void operator()(const f32x4 (&acc)[2][2][4][2], const Unit& u, int wr, int wc, int fr, int fq) const {
;     ...
;             for (int m = 0; m < 4; ++m) { PG8_GAS bf16_t* rowp = (PG8_GAS bf16_t*)O + (size_t)(row0 + ai * HALF + m * 16) * ldc + col0;
;                 const float rs = rsv[ai][m];
; #pragma unroll
;                 for (int bj = 0; bj < 2; ++bj) { f32x4 v0 = acc[ai][bj][m][0] * rs, v1 = acc[ai][bj][m][1] * rs;
;                     if (mode != 0) {
;                         const bool span = mode == 1 ? ((wc & 1) == 0 && (u.pn % rmod) < rlim) : (((u.pn * 8 + bj * 4 + wc) % 3) == 2);
;                         if (span) {
;                             const int pos = (row0 + ai * HALF + m * 16) & smask;
;                             const PG8_GAS f32x4* t4 = (const PG8_GAS f32x4*)((const PG8_GAS float*)tab + (mode == 1 ? (size_t)pos * 16 : (size_t)pos * 32 + 16 * (fq & 1)));
;                             const int dist = mode == 1 ? 16 : 32; const bool part = mode == 1 ? fq < 2 : true; const bool firsth = mode == 1 ? fq == 0 : fq < 2;
;                             const f32x4 c0 = t4[0], c1 = t4[1], c2 = t4[2], c3 = t4[3];
;                             f32x4 o0, o1;
; #pragma unroll
;                             for (int e = 0; e < 4; ++e) { o0[e] = __shfl_xor(v0[e], dist); o1[e] = __shfl_xor(v1[e], dist); }
;                             if (part) { const float sg = firsth ? -1.0f : 1.0f;
;                                 v0[0] = v0[0] * c0.x + sg * o0[0] * c0.y; v0[1] = v0[1] * c0.z + sg * o0[1] * c0.w; v0[2] = v0[2] * c1.x + sg * o0[2] * c1.y; v0[3] = v0[3] * c1.z + sg * o0[3] * c1.w;
;                                 v1[0] = v1[0] * c2.x + sg * o1[0] * c2.y; v1[1] = v1[1] * c2.z + sg * o1[1] * c2.w; v1[2] = v1[2] * c3.x + sg * o1[2] * c3.y; v1[3] = v1[3] * c3.z + sg * o1[3] * c3.w; }
;                         }
;                     }
;                     if (ACT == 1) {
; #pragma unroll
;                         for (int e = 0; e < 4; ++e) { float a = v0[e] > 0.f ? v0[e] : 0.f; v0[e] = a * a; float b = v1[e] > 0.f ? v1[e] : 0.f; v1[e] = b * b; } }
;                     u32x4 w; w.x = cvt_pk_bf16(v0[0], v0[1]); w.y = cvt_pk_bf16(v0[2], v0[3]); w.z = cvt_pk_bf16(v1[0], v1[1]); w.w = cvt_pk_bf16(v1[2], v1[3]);
;                     *(PG8_GAS u32x4*)(rowp + bj * HALF) = w; } }
.LBB0_543:
	s_waitcnt lgkmcnt(0)
	v_mad_u64_u32 v[72:73], s[40:41], v84, s67, 0
	v_ashrrev_i32_e32 v83, 31, v84
	v_mov_b32_e32 v82, v73
	v_mad_u64_u32 v[82:83], s[40:41], v83, s67, v[82:83]
	v_mov_b32_e32 v73, v82
	v_lshl_add_u64 v[72:73], v[72:73], 1, s[96:97]
	v_cvt_pk_bf16_f32 v76, v76, v77
	v_cvt_pk_bf16_f32 v77, v78, v79
	v_cvt_pk_bf16_f32 v78, v74, v75
	v_mov_b32_e32 v153, v152
	v_mov_b32_e32 v74, v152
	v_mov_b32_e32 v75, v152
	v_lshl_add_u64 v[72:73], v[120:121], 1, v[72:73]
	v_pk_mul_f32 v[70:71], v[70:71], v[74:75]
	v_pk_mul_f32 v[68:69], v[68:69], v[152:153]
	v_pk_mul_f32 v[66:67], v[66:67], v[74:75]
	s_cmp_lt_i32 s66, 1
	v_pk_mul_f32 v[64:65], v[64:65], v[152:153]
	v_cvt_pk_bf16_f32 v79, v80, v81
	global_store_dwordx4 v[72:73], v[76:79], off sc0 sc1
	s_cbranch_scc1 .LBB0_554
	s_cmp_lg_u32 s66, 1
	s_cbranch_scc0 .LBB0_546
	s_lshl_b32 s35, s26, 3
	s_or_b32 s35, s35, s12
	s_mul_hi_i32 s40, s35, 0x55555556
	s_lshr_b32 s41, s40, 31
	s_add_i32 s40, s40, s41
	s_mul_i32 s40, s40, 3
	s_sub_i32 s35, s35, s40
	s_cmp_eq_u32 s35, 2
	s_mov_b64 s[40:41], -1
	s_cselect_b64 s[44:45], -1, 0
	s_cbranch_execz .LBB0_547
	s_branch .LBB0_549

;     __device__ __forceinline__ void operator()(const f32x4 (&acc)[2][2][4][2], const Unit& u, int wr, int wc, int fr, int fq) const {
;     ...
;             for (int m = 0; m < 4; ++m) { PG8_GAS bf16_t* rowp = (PG8_GAS bf16_t*)O + (size_t)(row0 + ai * HALF + m * 16) * ldc + col0;
;                 const float rs = rsv[ai][m];
; #pragma unroll
;                 for (int bj = 0; bj < 2; ++bj) { f32x4 v0 = acc[ai][bj][m][0] * rs, v1 = acc[ai][bj][m][1] * rs;
;                     if (mode != 0) {
;                         const bool span = mode == 1 ? ((wc & 1) == 0 && (u.pn % rmod) < rlim) : (((u.pn * 8 + bj * 4 + wc) % 3) == 2);
;                         if (span) {
;                             const int pos = (row0 + ai * HALF + m * 16) & smask;
;                             const PG8_GAS f32x4* t4 = (const PG8_GAS f32x4*)((const PG8_GAS float*)tab + (mode == 1 ? (size_t)pos * 16 : (size_t)pos * 32 + 16 * (fq & 1)));
;                             const int dist = mode == 1 ? 16 : 32; const bool part = mode == 1 ? fq < 2 : true; const bool firsth = mode == 1 ? fq == 0 : fq < 2;
;                             const f32x4 c0 = t4[0], c1 = t4[1], c2 = t4[2], c3 = t4[3];
;                             f32x4 o0, o1;
; #pragma unroll
;                             for (int e = 0; e < 4; ++e) { o0[e] = __shfl_xor(v0[e], dist); o1[e] = __shfl_xor(v1[e], dist); }
;                             if (part) { const float sg = firsth ? -1.0f : 1.0f;
;                                 v0[0] = v0[0] * c0.x + sg * o0[0] * c0.y; v0[1] = v0[1] * c0.z + sg * o0[1] * c0.w; v0[2] = v0[2] * c1.x + sg * o0[2] * c1.y; v0[3] = v0[3] * c1.z + sg * o0[3] * c1.w;
;                                 v1[0] = v1[0] * c2.x + sg * o1[0] * c2.y; v1[1] = v1[1] * c2.z + sg * o1[1] * c2.w; v1[2] = v1[2] * c3.x + sg * o1[2] * c3.y; v1[3] = v1[3] * c3.z + sg * o1[3] * c3.w; }
;                         }
;                     }
;                     if (ACT == 1) {
; #pragma unroll
;                         for (int e = 0; e < 4; ++e) { float a = v0[e] > 0.f ? v0[e] : 0.f; v0[e] = a * a; float b = v1[e] > 0.f ? v1[e] : 0.f; v1[e] = b * b; } }
;                     u32x4 w; w.x = cvt_pk_bf16(v0[0], v0[1]); w.y = cvt_pk_bf16(v0[2], v0[3]); w.z = cvt_pk_bf16(v1[0], v1[1]); w.w = cvt_pk_bf16(v1[2], v1[3]);
;                     *(PG8_GAS u32x4*)(rowp + bj * HALF) = w; } }
.LBB0_554:
	v_cvt_pk_bf16_f32 v68, v68, v69
	v_cvt_pk_bf16_f32 v69, v70, v71
	v_cvt_pk_bf16_f32 v70, v64, v65
	v_cvt_pk_bf16_f32 v71, v66, v67
	global_store_dwordx4 v[72:73], v[68:71], off offset:256 sc0 sc1
	v_pk_mul_f32 v[62:63], v[62:63], v[150:151] op_sel_hi:[1,0]
	v_pk_mul_f32 v[60:61], v[60:61], v[150:151] op_sel_hi:[1,0]
	v_add_u32_e32 v68, 0x80, v142
	v_pk_mul_f32 v[64:65], v[58:59], v[150:151] op_sel_hi:[1,0]
	s_cmp_lt_i32 s66, 1
	v_pk_mul_f32 v[58:59], v[56:57], v[150:151] op_sel_hi:[1,0]
	s_cbranch_scc1 .LBB0_565
	s_cmp_lg_u32 s66, 1
	s_cbranch_scc0 .LBB0_557
	s_lshl_b32 s35, s26, 3
	s_or_b32 s35, s35, s50
	s_mul_hi_i32 s40, s35, 0x55555556
	s_lshr_b32 s41, s40, 31
	s_add_i32 s40, s40, s41
	s_mul_i32 s40, s40, 3
	s_sub_i32 s35, s35, s40
	s_cmp_eq_u32 s35, 2
	s_mov_b64 s[40:41], -1
	s_cselect_b64 s[44:45], -1, 0
	s_cbranch_execz .LBB0_558
	s_branch .LBB0_560

;     __device__ __forceinline__ void operator()(const f32x4 (&acc)[2][2][4][2], const Unit& u, int wr, int wc, int fr, int fq) const {
;     ...
;             for (int m = 0; m < 4; ++m) { PG8_GAS bf16_t* rowp = (PG8_GAS bf16_t*)O + (size_t)(row0 + ai * HALF + m * 16) * ldc + col0;
;                 const float rs = rsv[ai][m];
; #pragma unroll
;                 for (int bj = 0; bj < 2; ++bj) { f32x4 v0 = acc[ai][bj][m][0] * rs, v1 = acc[ai][bj][m][1] * rs;
;                     if (mode != 0) {
;                         const bool span = mode == 1 ? ((wc & 1) == 0 && (u.pn % rmod) < rlim) : (((u.pn * 8 + bj * 4 + wc) % 3) == 2);
;                         if (span) {
;                             const int pos = (row0 + ai * HALF + m * 16) & smask;
;                             const PG8_GAS f32x4* t4 = (const PG8_GAS f32x4*)((const PG8_GAS float*)tab + (mode == 1 ? (size_t)pos * 16 : (size_t)pos * 32 + 16 * (fq & 1)));
;                             const int dist = mode == 1 ? 16 : 32; const bool part = mode == 1 ? fq < 2 : true; const bool firsth = mode == 1 ? fq == 0 : fq < 2;
;                             const f32x4 c0 = t4[0], c1 = t4[1], c2 = t4[2], c3 = t4[3];
;                             f32x4 o0, o1;
; #pragma unroll
;                             for (int e = 0; e < 4; ++e) { o0[e] = __shfl_xor(v0[e], dist); o1[e] = __shfl_xor(v1[e], dist); }
;                             if (part) { const float sg = firsth ? -1.0f : 1.0f;
;                                 v0[0] = v0[0] * c0.x + sg * o0[0] * c0.y; v0[1] = v0[1] * c0.z + sg * o0[1] * c0.w; v0[2] = v0[2] * c1.x + sg * o0[2] * c1.y; v0[3] = v0[3] * c1.z + sg * o0[3] * c1.w;
;                                 v1[0] = v1[0] * c2.x + sg * o1[0] * c2.y; v1[1] = v1[1] * c2.z + sg * o1[1] * c2.w; v1[2] = v1[2] * c3.x + sg * o1[2] * c3.y; v1[3] = v1[3] * c3.z + sg * o1[3] * c3.w; }
;                         }
;                     }
;                     if (ACT == 1) {
; #pragma unroll
;                         for (int e = 0; e < 4; ++e) { float a = v0[e] > 0.f ? v0[e] : 0.f; v0[e] = a * a; float b = v1[e] > 0.f ? v1[e] : 0.f; v1[e] = b * b; } }
;                     u32x4 w; w.x = cvt_pk_bf16(v0[0], v0[1]); w.y = cvt_pk_bf16(v0[2], v0[3]); w.z = cvt_pk_bf16(v1[0], v1[1]); w.w = cvt_pk_bf16(v1[2], v1[3]);
;                     *(PG8_GAS u32x4*)(rowp + bj * HALF) = w; } }
.LBB0_565:
	s_waitcnt lgkmcnt(0)
	v_mad_u64_u32 v[56:57], s[40:41], v68, s67, 0
	v_ashrrev_i32_e32 v67, 31, v68
	v_mov_b32_e32 v66, v57
	v_mad_u64_u32 v[66:67], s[40:41], v67, s67, v[66:67]
	v_mov_b32_e32 v57, v66
	v_lshl_add_u64 v[56:57], v[56:57], 1, s[96:97]
	v_cvt_pk_bf16_f32 v60, v60, v61
	v_cvt_pk_bf16_f32 v61, v62, v63
	v_cvt_pk_bf16_f32 v62, v58, v59
	v_mov_b32_e32 v151, v150
	v_mov_b32_e32 v58, v150
	v_mov_b32_e32 v59, v150
	v_lshl_add_u64 v[56:57], v[120:121], 1, v[56:57]
	v_pk_mul_f32 v[54:55], v[54:55], v[58:59]
	v_pk_mul_f32 v[52:53], v[52:53], v[150:151]
	v_pk_mul_f32 v[50:51], v[50:51], v[58:59]
	s_cmp_lt_i32 s66, 1
	v_pk_mul_f32 v[48:49], v[48:49], v[150:151]
	v_cvt_pk_bf16_f32 v63, v64, v65
	global_store_dwordx4 v[56:57], v[60:63], off sc0 sc1
	s_cbranch_scc1 .LBB0_576
	s_cmp_lg_u32 s66, 1
	s_cbranch_scc0 .LBB0_568
	s_lshl_b32 s35, s26, 3
	s_or_b32 s35, s35, s12
	s_mul_hi_i32 s40, s35, 0x55555556
	s_lshr_b32 s41, s40, 31
	s_add_i32 s40, s40, s41
	s_mul_i32 s40, s40, 3
	s_sub_i32 s35, s35, s40
	s_cmp_eq_u32 s35, 2
	s_mov_b64 s[40:41], -1
	s_cselect_b64 s[44:45], -1, 0
	s_cbranch_execz .LBB0_569
	s_branch .LBB0_571

;     __device__ __forceinline__ void operator()(const f32x4 (&acc)[2][2][4][2], const Unit& u, int wr, int wc, int fr, int fq) const {
;     ...
;             for (int m = 0; m < 4; ++m) { PG8_GAS bf16_t* rowp = (PG8_GAS bf16_t*)O + (size_t)(row0 + ai * HALF + m * 16) * ldc + col0;
;                 const float rs = rsv[ai][m];
; #pragma unroll
;                 for (int bj = 0; bj < 2; ++bj) { f32x4 v0 = acc[ai][bj][m][0] * rs, v1 = acc[ai][bj][m][1] * rs;
;                     if (mode != 0) {
;                         const bool span = mode == 1 ? ((wc & 1) == 0 && (u.pn % rmod) < rlim) : (((u.pn * 8 + bj * 4 + wc) % 3) == 2);
;                         if (span) {
;                             const int pos = (row0 + ai * HALF + m * 16) & smask;
;                             const PG8_GAS f32x4* t4 = (const PG8_GAS f32x4*)((const PG8_GAS float*)tab + (mode == 1 ? (size_t)pos * 16 : (size_t)pos * 32 + 16 * (fq & 1)));
;                             const int dist = mode == 1 ? 16 : 32; const bool part = mode == 1 ? fq < 2 : true; const bool firsth = mode == 1 ? fq == 0 : fq < 2;
;                             const f32x4 c0 = t4[0], c1 = t4[1], c2 = t4[2], c3 = t4[3];
;                             f32x4 o0, o1;
; #pragma unroll
;                             for (int e = 0; e < 4; ++e) { o0[e] = __shfl_xor(v0[e], dist); o1[e] = __shfl_xor(v1[e], dist); }
;                             if (part) { const float sg = firsth ? -1.0f : 1.0f;
;                                 v0[0] = v0[0] * c0.x + sg * o0[0] * c0.y; v0[1] = v0[1] * c0.z + sg * o0[1] * c0.w; v0[2] = v0[2] * c1.x + sg * o0[2] * c1.y; v0[3] = v0[3] * c1.z + sg * o0[3] * c1.w;
;                                 v1[0] = v1[0] * c2.x + sg * o1[0] * c2.y; v1[1] = v1[1] * c2.z + sg * o1[1] * c2.w; v1[2] = v1[2] * c3.x + sg * o1[2] * c3.y; v1[3] = v1[3] * c3.z + sg * o1[3] * c3.w; }
;                         }
;                     }
;                     if (ACT == 1) {
; #pragma unroll
;                         for (int e = 0; e < 4; ++e) { float a = v0[e] > 0.f ? v0[e] : 0.f; v0[e] = a * a; float b = v1[e] > 0.f ? v1[e] : 0.f; v1[e] = b * b; } }
;                     u32x4 w; w.x = cvt_pk_bf16(v0[0], v0[1]); w.y = cvt_pk_bf16(v0[2], v0[3]); w.z = cvt_pk_bf16(v1[0], v1[1]); w.w = cvt_pk_bf16(v1[2], v1[3]);
;                     *(PG8_GAS u32x4*)(rowp + bj * HALF) = w; } }
.LBB0_576:
	v_cvt_pk_bf16_f32 v52, v52, v53
	v_cvt_pk_bf16_f32 v53, v54, v55
	v_cvt_pk_bf16_f32 v54, v48, v49
	v_cvt_pk_bf16_f32 v55, v50, v51
	global_store_dwordx4 v[56:57], v[52:55], off offset:256 sc0 sc1
	v_pk_mul_f32 v[46:47], v[46:47], v[148:149] op_sel_hi:[1,0]
	v_pk_mul_f32 v[44:45], v[44:45], v[148:149] op_sel_hi:[1,0]
	v_add_u32_e32 v52, 0x90, v142
	v_pk_mul_f32 v[48:49], v[42:43], v[148:149] op_sel_hi:[1,0]
	s_cmp_lt_i32 s66, 1
	v_pk_mul_f32 v[42:43], v[40:41], v[148:149] op_sel_hi:[1,0]
	s_cbranch_scc1 .LBB0_587
	s_cmp_lg_u32 s66, 1
	s_cbranch_scc0 .LBB0_579
	s_lshl_b32 s35, s26, 3
	s_or_b32 s35, s35, s50
	s_mul_hi_i32 s40, s35, 0x55555556
	s_lshr_b32 s41, s40, 31
	s_add_i32 s40, s40, s41
	s_mul_i32 s40, s40, 3
	s_sub_i32 s35, s35, s40
	s_cmp_eq_u32 s35, 2
	s_mov_b64 s[40:41], -1
	s_cselect_b64 s[44:45], -1, 0
	s_cbranch_execz .LBB0_580
	s_branch .LBB0_582

;     __device__ __forceinline__ void operator()(const f32x4 (&acc)[2][2][4][2], const Unit& u, int wr, int wc, int fr, int fq) const {
;     ...
;             for (int m = 0; m < 4; ++m) { PG8_GAS bf16_t* rowp = (PG8_GAS bf16_t*)O + (size_t)(row0 + ai * HALF + m * 16) * ldc + col0;
;                 const float rs = rsv[ai][m];
; #pragma unroll
;                 for (int bj = 0; bj < 2; ++bj) { f32x4 v0 = acc[ai][bj][m][0] * rs, v1 = acc[ai][bj][m][1] * rs;
;                     if (mode != 0) {
;                         const bool span = mode == 1 ? ((wc & 1) == 0 && (u.pn % rmod) < rlim) : (((u.pn * 8 + bj * 4 + wc) % 3) == 2);
;                         if (span) {
;                             const int pos = (row0 + ai * HALF + m * 16) & smask;
;                             const PG8_GAS f32x4* t4 = (const PG8_GAS f32x4*)((const PG8_GAS float*)tab + (mode == 1 ? (size_t)pos * 16 : (size_t)pos * 32 + 16 * (fq & 1)));
;                             const int dist = mode == 1 ? 16 : 32; const bool part = mode == 1 ? fq < 2 : true; const bool firsth = mode == 1 ? fq == 0 : fq < 2;
;                             const f32x4 c0 = t4[0], c1 = t4[1], c2 = t4[2], c3 = t4[3];
;                             f32x4 o0, o1;
; #pragma unroll
;                             for (int e = 0; e < 4; ++e) { o0[e] = __shfl_xor(v0[e], dist); o1[e] = __shfl_xor(v1[e], dist); }
;                             if (part) { const float sg = firsth ? -1.0f : 1.0f;
;                                 v0[0] = v0[0] * c0.x + sg * o0[0] * c0.y; v0[1] = v0[1] * c0.z + sg * o0[1] * c0.w; v0[2] = v0[2] * c1.x + sg * o0[2] * c1.y; v0[3] = v0[3] * c1.z + sg * o0[3] * c1.w;
;                                 v1[0] = v1[0] * c2.x + sg * o1[0] * c2.y; v1[1] = v1[1] * c2.z + sg * o1[1] * c2.w; v1[2] = v1[2] * c3.x + sg * o1[2] * c3.y; v1[3] = v1[3] * c3.z + sg * o1[3] * c3.w; }
;                         }
;                     }
;                     if (ACT == 1) {
; #pragma unroll
;                         for (int e = 0; e < 4; ++e) { float a = v0[e] > 0.f ? v0[e] : 0.f; v0[e] = a * a; float b = v1[e] > 0.f ? v1[e] : 0.f; v1[e] = b * b; } }
;                     u32x4 w; w.x = cvt_pk_bf16(v0[0], v0[1]); w.y = cvt_pk_bf16(v0[2], v0[3]); w.z = cvt_pk_bf16(v1[0], v1[1]); w.w = cvt_pk_bf16(v1[2], v1[3]);
;                     *(PG8_GAS u32x4*)(rowp + bj * HALF) = w; } }
.LBB0_587:
	s_waitcnt lgkmcnt(0)
	v_mad_u64_u32 v[40:41], s[40:41], v52, s67, 0
	v_ashrrev_i32_e32 v51, 31, v52
	v_mov_b32_e32 v50, v41
	v_mad_u64_u32 v[50:51], s[40:41], v51, s67, v[50:51]
	v_mov_b32_e32 v41, v50
	v_lshl_add_u64 v[40:41], v[40:41], 1, s[96:97]
	v_cvt_pk_bf16_f32 v44, v44, v45
	v_cvt_pk_bf16_f32 v45, v46, v47
	v_cvt_pk_bf16_f32 v46, v42, v43
	v_mov_b32_e32 v149, v148
	v_mov_b32_e32 v42, v148
	v_mov_b32_e32 v43, v148
	v_lshl_add_u64 v[40:41], v[120:121], 1, v[40:41]
	v_pk_mul_f32 v[38:39], v[38:39], v[42:43]
	v_pk_mul_f32 v[36:37], v[36:37], v[148:149]
	v_pk_mul_f32 v[34:35], v[34:35], v[42:43]
	s_cmp_lt_i32 s66, 1
	v_pk_mul_f32 v[32:33], v[32:33], v[148:149]
	v_cvt_pk_bf16_f32 v47, v48, v49
	global_store_dwordx4 v[40:41], v[44:47], off sc0 sc1
	s_cbranch_scc1 .LBB0_598
	s_cmp_lg_u32 s66, 1
	s_cbranch_scc0 .LBB0_590
	s_lshl_b32 s35, s26, 3
	s_or_b32 s35, s35, s12
	s_mul_hi_i32 s40, s35, 0x55555556
	s_lshr_b32 s41, s40, 31
	s_add_i32 s40, s40, s41
	s_mul_i32 s40, s40, 3
	s_sub_i32 s35, s35, s40
	s_cmp_eq_u32 s35, 2
	s_mov_b64 s[40:41], -1
	s_cselect_b64 s[44:45], -1, 0
	s_cbranch_execz .LBB0_591
	s_branch .LBB0_593

;     __device__ __forceinline__ void operator()(const f32x4 (&acc)[2][2][4][2], const Unit& u, int wr, int wc, int fr, int fq) const {
;     ...
;             for (int m = 0; m < 4; ++m) { PG8_GAS bf16_t* rowp = (PG8_GAS bf16_t*)O + (size_t)(row0 + ai * HALF + m * 16) * ldc + col0;
;                 const float rs = rsv[ai][m];
; #pragma unroll
;                 for (int bj = 0; bj < 2; ++bj) { f32x4 v0 = acc[ai][bj][m][0] * rs, v1 = acc[ai][bj][m][1] * rs;
;                     if (mode != 0) {
;                         const bool span = mode == 1 ? ((wc & 1) == 0 && (u.pn % rmod) < rlim) : (((u.pn * 8 + bj * 4 + wc) % 3) == 2);
;                         if (span) {
;                             const int pos = (row0 + ai * HALF + m * 16) & smask;
;                             const PG8_GAS f32x4* t4 = (const PG8_GAS f32x4*)((const PG8_GAS float*)tab + (mode == 1 ? (size_t)pos * 16 : (size_t)pos * 32 + 16 * (fq & 1)));
;                             const int dist = mode == 1 ? 16 : 32; const bool part = mode == 1 ? fq < 2 : true; const bool firsth = mode == 1 ? fq == 0 : fq < 2;
;                             const f32x4 c0 = t4[0], c1 = t4[1], c2 = t4[2], c3 = t4[3];
;                             f32x4 o0, o1;
; #pragma unroll
;                             for (int e = 0; e < 4; ++e) { o0[e] = __shfl_xor(v0[e], dist); o1[e] = __shfl_xor(v1[e], dist); }
;                             if (part) { const float sg = firsth ? -1.0f : 1.0f;
;                                 v0[0] = v0[0] * c0.x + sg * o0[0] * c0.y; v0[1] = v0[1] * c0.z + sg * o0[1] * c0.w; v0[2] = v0[2] * c1.x + sg * o0[2] * c1.y; v0[3] = v0[3] * c1.z + sg * o0[3] * c1.w;
;                                 v1[0] = v1[0] * c2.x + sg * o1[0] * c2.y; v1[1] = v1[1] * c2.z + sg * o1[1] * c2.w; v1[2] = v1[2] * c3.x + sg * o1[2] * c3.y; v1[3] = v1[3] * c3.z + sg * o1[3] * c3.w; }
;                         }
;                     }
;                     if (ACT == 1) {
; #pragma unroll
;                         for (int e = 0; e < 4; ++e) { float a = v0[e] > 0.f ? v0[e] : 0.f; v0[e] = a * a; float b = v1[e] > 0.f ? v1[e] : 0.f; v1[e] = b * b; } }
;                     u32x4 w; w.x = cvt_pk_bf16(v0[0], v0[1]); w.y = cvt_pk_bf16(v0[2], v0[3]); w.z = cvt_pk_bf16(v1[0], v1[1]); w.w = cvt_pk_bf16(v1[2], v1[3]);
;                     *(PG8_GAS u32x4*)(rowp + bj * HALF) = w; } }
.LBB0_598:
	v_cvt_pk_bf16_f32 v36, v36, v37
	v_cvt_pk_bf16_f32 v37, v38, v39
	v_cvt_pk_bf16_f32 v38, v32, v33
	v_cvt_pk_bf16_f32 v39, v34, v35
	global_store_dwordx4 v[40:41], v[36:39], off offset:256 sc0 sc1
	v_pk_mul_f32 v[30:31], v[30:31], v[146:147] op_sel_hi:[1,0]
	v_pk_mul_f32 v[28:29], v[28:29], v[146:147] op_sel_hi:[1,0]
	v_add_u32_e32 v36, 0xa0, v142
	v_pk_mul_f32 v[32:33], v[26:27], v[146:147] op_sel_hi:[1,0]
	s_cmp_lt_i32 s66, 1
	v_pk_mul_f32 v[26:27], v[24:25], v[146:147] op_sel_hi:[1,0]
	s_cbranch_scc1 .LBB0_609
	s_cmp_lg_u32 s66, 1
	s_cbranch_scc0 .LBB0_601
	s_lshl_b32 s35, s26, 3
	s_or_b32 s35, s35, s50
	s_mul_hi_i32 s40, s35, 0x55555556
	s_lshr_b32 s41, s40, 31
	s_add_i32 s40, s40, s41
	s_mul_i32 s40, s40, 3
	s_sub_i32 s35, s35, s40
	s_cmp_eq_u32 s35, 2
	s_mov_b64 s[40:41], -1
	s_cselect_b64 s[44:45], -1, 0
	s_cbranch_execz .LBB0_602
	s_branch .LBB0_604

;     __device__ __forceinline__ void operator()(const f32x4 (&acc)[2][2][4][2], const Unit& u, int wr, int wc, int fr, int fq) const {
;     ...
;             for (int m = 0; m < 4; ++m) { PG8_GAS bf16_t* rowp = (PG8_GAS bf16_t*)O + (size_t)(row0 + ai * HALF + m * 16) * ldc + col0;
;                 const float rs = rsv[ai][m];
; #pragma unroll
;                 for (int bj = 0; bj < 2; ++bj) { f32x4 v0 = acc[ai][bj][m][0] * rs, v1 = acc[ai][bj][m][1] * rs;
;                     if (mode != 0) {
;                         const bool span = mode == 1 ? ((wc & 1) == 0 && (u.pn % rmod) < rlim) : (((u.pn * 8 + bj * 4 + wc) % 3) == 2);
;                         if (span) {
;                             const int pos = (row0 + ai * HALF + m * 16) & smask;
;                             const PG8_GAS f32x4* t4 = (const PG8_GAS f32x4*)((const PG8_GAS float*)tab + (mode == 1 ? (size_t)pos * 16 : (size_t)pos * 32 + 16 * (fq & 1)));
;                             const int dist = mode == 1 ? 16 : 32; const bool part = mode == 1 ? fq < 2 : true; const bool firsth = mode == 1 ? fq == 0 : fq < 2;
;                             const f32x4 c0 = t4[0], c1 = t4[1], c2 = t4[2], c3 = t4[3];
;                             f32x4 o0, o1;
; #pragma unroll
;                             for (int e = 0; e < 4; ++e) { o0[e] = __shfl_xor(v0[e], dist); o1[e] = __shfl_xor(v1[e], dist); }
;                             if (part) { const float sg = firsth ? -1.0f : 1.0f;
;                                 v0[0] = v0[0] * c0.x + sg * o0[0] * c0.y; v0[1] = v0[1] * c0.z + sg * o0[1] * c0.w; v0[2] = v0[2] * c1.x + sg * o0[2] * c1.y; v0[3] = v0[3] * c1.z + sg * o0[3] * c1.w;
;                                 v1[0] = v1[0] * c2.x + sg * o1[0] * c2.y; v1[1] = v1[1] * c2.z + sg * o1[1] * c2.w; v1[2] = v1[2] * c3.x + sg * o1[2] * c3.y; v1[3] = v1[3] * c3.z + sg * o1[3] * c3.w; }
;                         }
;                     }
;                     if (ACT == 1) {
; #pragma unroll
;                         for (int e = 0; e < 4; ++e) { float a = v0[e] > 0.f ? v0[e] : 0.f; v0[e] = a * a; float b = v1[e] > 0.f ? v1[e] : 0.f; v1[e] = b * b; } }
;                     u32x4 w; w.x = cvt_pk_bf16(v0[0], v0[1]); w.y = cvt_pk_bf16(v0[2], v0[3]); w.z = cvt_pk_bf16(v1[0], v1[1]); w.w = cvt_pk_bf16(v1[2], v1[3]);
;                     *(PG8_GAS u32x4*)(rowp + bj * HALF) = w; } }
.LBB0_609:
	s_waitcnt lgkmcnt(0)
	v_mad_u64_u32 v[24:25], s[40:41], v36, s67, 0
	v_ashrrev_i32_e32 v35, 31, v36
	v_mov_b32_e32 v34, v25
	v_mad_u64_u32 v[34:35], s[40:41], v35, s67, v[34:35]
	v_mov_b32_e32 v25, v34
	v_lshl_add_u64 v[24:25], v[24:25], 1, s[96:97]
	v_cvt_pk_bf16_f32 v28, v28, v29
	v_cvt_pk_bf16_f32 v29, v30, v31
	v_cvt_pk_bf16_f32 v30, v26, v27
	v_mov_b32_e32 v147, v146
	v_mov_b32_e32 v26, v146
	v_mov_b32_e32 v27, v146
	v_lshl_add_u64 v[24:25], v[120:121], 1, v[24:25]
	v_pk_mul_f32 v[22:23], v[22:23], v[26:27]
	v_pk_mul_f32 v[20:21], v[20:21], v[146:147]
	v_pk_mul_f32 v[18:19], v[18:19], v[26:27]
	s_cmp_lt_i32 s66, 1
	v_pk_mul_f32 v[16:17], v[16:17], v[146:147]
	v_cvt_pk_bf16_f32 v31, v32, v33
	global_store_dwordx4 v[24:25], v[28:31], off sc0 sc1
	s_cbranch_scc1 .LBB0_620
	s_cmp_lg_u32 s66, 1
	s_cbranch_scc0 .LBB0_612
	s_lshl_b32 s35, s26, 3
	s_or_b32 s35, s35, s12
	s_mul_hi_i32 s40, s35, 0x55555556
	s_lshr_b32 s41, s40, 31
	s_add_i32 s40, s40, s41
	s_mul_i32 s40, s40, 3
	s_sub_i32 s35, s35, s40
	s_cmp_eq_u32 s35, 2
	s_mov_b64 s[40:41], -1
	s_cselect_b64 s[44:45], -1, 0
	s_cbranch_execz .LBB0_613
	s_branch .LBB0_615

;     __device__ __forceinline__ void operator()(const f32x4 (&acc)[2][2][4][2], const Unit& u, int wr, int wc, int fr, int fq) const {
;     ...
;             for (int m = 0; m < 4; ++m) { PG8_GAS bf16_t* rowp = (PG8_GAS bf16_t*)O + (size_t)(row0 + ai * HALF + m * 16) * ldc + col0;
;                 const float rs = rsv[ai][m];
; #pragma unroll
;                 for (int bj = 0; bj < 2; ++bj) { f32x4 v0 = acc[ai][bj][m][0] * rs, v1 = acc[ai][bj][m][1] * rs;
;                     if (mode != 0) {
;                         const bool span = mode == 1 ? ((wc & 1) == 0 && (u.pn % rmod) < rlim) : (((u.pn * 8 + bj * 4 + wc) % 3) == 2);
;                         if (span) {
;                             const int pos = (row0 + ai * HALF + m * 16) & smask;
;                             const PG8_GAS f32x4* t4 = (const PG8_GAS f32x4*)((const PG8_GAS float*)tab + (mode == 1 ? (size_t)pos * 16 : (size_t)pos * 32 + 16 * (fq & 1)));
;                             const int dist = mode == 1 ? 16 : 32; const bool part = mode == 1 ? fq < 2 : true; const bool firsth = mode == 1 ? fq == 0 : fq < 2;
;                             const f32x4 c0 = t4[0], c1 = t4[1], c2 = t4[2], c3 = t4[3];
;                             f32x4 o0, o1;
; #pragma unroll
;                             for (int e = 0; e < 4; ++e) { o0[e] = __shfl_xor(v0[e], dist); o1[e] = __shfl_xor(v1[e], dist); }
;                             if (part) { const float sg = firsth ? -1.0f : 1.0f;
;                                 v0[0] = v0[0] * c0.x + sg * o0[0] * c0.y; v0[1] = v0[1] * c0.z + sg * o0[1] * c0.w; v0[2] = v0[2] * c1.x + sg * o0[2] * c1.y; v0[3] = v0[3] * c1.z + sg * o0[3] * c1.w;
;                                 v1[0] = v1[0] * c2.x + sg * o1[0] * c2.y; v1[1] = v1[1] * c2.z + sg * o1[1] * c2.w; v1[2] = v1[2] * c3.x + sg * o1[2] * c3.y; v1[3] = v1[3] * c3.z + sg * o1[3] * c3.w; }
;                         }
;                     }
;                     if (ACT == 1) {
; #pragma unroll
;                         for (int e = 0; e < 4; ++e) { float a = v0[e] > 0.f ? v0[e] : 0.f; v0[e] = a * a; float b = v1[e] > 0.f ? v1[e] : 0.f; v1[e] = b * b; } }
;                     u32x4 w; w.x = cvt_pk_bf16(v0[0], v0[1]); w.y = cvt_pk_bf16(v0[2], v0[3]); w.z = cvt_pk_bf16(v1[0], v1[1]); w.w = cvt_pk_bf16(v1[2], v1[3]);
;                     *(PG8_GAS u32x4*)(rowp + bj * HALF) = w; } }
.LBB0_620:
	v_cvt_pk_bf16_f32 v20, v20, v21
	v_cvt_pk_bf16_f32 v21, v22, v23
	v_cvt_pk_bf16_f32 v22, v16, v17
	v_cvt_pk_bf16_f32 v23, v18, v19
	global_store_dwordx4 v[24:25], v[20:23], off offset:256 sc0 sc1
	v_pk_mul_f32 v[14:15], v[14:15], v[144:145] op_sel_hi:[1,0]
	v_pk_mul_f32 v[12:13], v[12:13], v[144:145] op_sel_hi:[1,0]
	v_add_u32_e32 v20, 0xb0, v142
	v_pk_mul_f32 v[16:17], v[10:11], v[144:145] op_sel_hi:[1,0]
	s_cmp_lt_i32 s66, 1
	v_pk_mul_f32 v[10:11], v[8:9], v[144:145] op_sel_hi:[1,0]
	s_cbranch_scc1 .LBB0_631
	s_cmp_lg_u32 s66, 1
	s_cbranch_scc0 .LBB0_623
	s_lshl_b32 s35, s26, 3
	s_or_b32 s35, s35, s50
	s_mul_hi_i32 s40, s35, 0x55555556
	s_lshr_b32 s41, s40, 31
	s_add_i32 s40, s40, s41
	s_mul_i32 s40, s40, 3
	s_sub_i32 s35, s35, s40
	s_cmp_eq_u32 s35, 2
	s_mov_b64 s[40:41], -1
	s_cselect_b64 s[44:45], -1, 0
	s_cbranch_execz .LBB0_624
	s_branch .LBB0_626

;     __device__ __forceinline__ void operator()(const f32x4 (&acc)[2][2][4][2], const Unit& u, int wr, int wc, int fr, int fq) const {
;     ...
;             for (int m = 0; m < 4; ++m) { PG8_GAS bf16_t* rowp = (PG8_GAS bf16_t*)O + (size_t)(row0 + ai * HALF + m * 16) * ldc + col0;
;                 const float rs = rsv[ai][m];
; #pragma unroll
;                 for (int bj = 0; bj < 2; ++bj) { f32x4 v0 = acc[ai][bj][m][0] * rs, v1 = acc[ai][bj][m][1] * rs;
;                     if (mode != 0) {
;                         const bool span = mode == 1 ? ((wc & 1) == 0 && (u.pn % rmod) < rlim) : (((u.pn * 8 + bj * 4 + wc) % 3) == 2);
;                         if (span) {
;                             const int pos = (row0 + ai * HALF + m * 16) & smask;
;                             const PG8_GAS f32x4* t4 = (const PG8_GAS f32x4*)((const PG8_GAS float*)tab + (mode == 1 ? (size_t)pos * 16 : (size_t)pos * 32 + 16 * (fq & 1)));
;                             const int dist = mode == 1 ? 16 : 32; const bool part = mode == 1 ? fq < 2 : true; const bool firsth = mode == 1 ? fq == 0 : fq < 2;
;                             const f32x4 c0 = t4[0], c1 = t4[1], c2 = t4[2], c3 = t4[3];
;                             f32x4 o0, o1;
; #pragma unroll
;                             for (int e = 0; e < 4; ++e) { o0[e] = __shfl_xor(v0[e], dist); o1[e] = __shfl_xor(v1[e], dist); }
;                             if (part) { const float sg = firsth ? -1.0f : 1.0f;
;                                 v0[0] = v0[0] * c0.x + sg * o0[0] * c0.y; v0[1] = v0[1] * c0.z + sg * o0[1] * c0.w; v0[2] = v0[2] * c1.x + sg * o0[2] * c1.y; v0[3] = v0[3] * c1.z + sg * o0[3] * c1.w;
;                                 v1[0] = v1[0] * c2.x + sg * o1[0] * c2.y; v1[1] = v1[1] * c2.z + sg * o1[1] * c2.w; v1[2] = v1[2] * c3.x + sg * o1[2] * c3.y; v1[3] = v1[3] * c3.z + sg * o1[3] * c3.w; }
;                         }
;                     }
;                     if (ACT == 1) {
; #pragma unroll
;                         for (int e = 0; e < 4; ++e) { float a = v0[e] > 0.f ? v0[e] : 0.f; v0[e] = a * a; float b = v1[e] > 0.f ? v1[e] : 0.f; v1[e] = b * b; } }
;                     u32x4 w; w.x = cvt_pk_bf16(v0[0], v0[1]); w.y = cvt_pk_bf16(v0[2], v0[3]); w.z = cvt_pk_bf16(v1[0], v1[1]); w.w = cvt_pk_bf16(v1[2], v1[3]);
;                     *(PG8_GAS u32x4*)(rowp + bj * HALF) = w; } }
.LBB0_631:
	s_waitcnt lgkmcnt(0)
	v_mad_u64_u32 v[8:9], s[40:41], v20, s67, 0
	v_ashrrev_i32_e32 v19, 31, v20
	v_mov_b32_e32 v18, v9
	v_mad_u64_u32 v[18:19], s[40:41], v19, s67, v[18:19]
	v_mov_b32_e32 v9, v18
	v_lshl_add_u64 v[8:9], v[8:9], 1, s[96:97]
	v_cvt_pk_bf16_f32 v12, v12, v13
	v_cvt_pk_bf16_f32 v13, v14, v15
	v_cvt_pk_bf16_f32 v14, v10, v11
	v_mov_b32_e32 v145, v144
	v_mov_b32_e32 v10, v144
	v_mov_b32_e32 v11, v144
	v_lshl_add_u64 v[8:9], v[120:121], 1, v[8:9]
	v_pk_mul_f32 v[6:7], v[6:7], v[10:11]
	v_pk_mul_f32 v[4:5], v[4:5], v[144:145]
	v_pk_mul_f32 v[2:3], v[2:3], v[10:11]
	s_cmp_lt_i32 s66, 1
	v_pk_mul_f32 v[0:1], v[0:1], v[144:145]
	v_cvt_pk_bf16_f32 v15, v16, v17
	global_store_dwordx4 v[8:9], v[12:15], off sc0 sc1
	s_cbranch_scc1 .LBB0_642
	s_cmp_lg_u32 s66, 1
	s_cbranch_scc0 .LBB0_634
	s_lshl_b32 s35, s26, 3
	s_or_b32 s35, s35, s12
	s_mul_hi_i32 s40, s35, 0x55555556
	s_lshr_b32 s41, s40, 31
	s_add_i32 s40, s40, s41
	s_mul_i32 s40, s40, 3
	s_sub_i32 s35, s35, s40
	s_cmp_eq_u32 s35, 2
	s_mov_b64 s[40:41], -1
	s_cselect_b64 s[44:45], -1, 0
	s_cbranch_execz .LBB0_635
	s_branch .LBB0_637

;     __device__ __forceinline__ void operator()(const f32x4 (&acc)[2][2][4][2], const Unit& u, int wr, int wc, int fr, int fq) const {
;     ...
;             for (int m = 0; m < 4; ++m) { PG8_GAS bf16_t* rowp = (PG8_GAS bf16_t*)O + (size_t)(row0 + ai * HALF + m * 16) * ldc + col0;
;                 const float rs = rsv[ai][m];
; #pragma unroll
;                 for (int bj = 0; bj < 2; ++bj) { f32x4 v0 = acc[ai][bj][m][0] * rs, v1 = acc[ai][bj][m][1] * rs;
;                     if (mode != 0) {
;                         const bool span = mode == 1 ? ((wc & 1) == 0 && (u.pn % rmod) < rlim) : (((u.pn * 8 + bj * 4 + wc) % 3) == 2);
;                         if (span) {
;                             const int pos = (row0 + ai * HALF + m * 16) & smask;
;                             const PG8_GAS f32x4* t4 = (const PG8_GAS f32x4*)((const PG8_GAS float*)tab + (mode == 1 ? (size_t)pos * 16 : (size_t)pos * 32 + 16 * (fq & 1)));
;                             const int dist = mode == 1 ? 16 : 32; const bool part = mode == 1 ? fq < 2 : true; const bool firsth = mode == 1 ? fq == 0 : fq < 2;
;                             const f32x4 c0 = t4[0], c1 = t4[1], c2 = t4[2], c3 = t4[3];
;                             f32x4 o0, o1;
; #pragma unroll
;                             for (int e = 0; e < 4; ++e) { o0[e] = __shfl_xor(v0[e], dist); o1[e] = __shfl_xor(v1[e], dist); }
;                             if (part) { const float sg = firsth ? -1.0f : 1.0f;
;                                 v0[0] = v0[0] * c0.x + sg * o0[0] * c0.y; v0[1] = v0[1] * c0.z + sg * o0[1] * c0.w; v0[2] = v0[2] * c1.x + sg * o0[2] * c1.y; v0[3] = v0[3] * c1.z + sg * o0[3] * c1.w;
;                                 v1[0] = v1[0] * c2.x + sg * o1[0] * c2.y; v1[1] = v1[1] * c2.z + sg * o1[1] * c2.w; v1[2] = v1[2] * c3.x + sg * o1[2] * c3.y; v1[3] = v1[3] * c3.z + sg * o1[3] * c3.w; }
;                         }
;                     }
;                     if (ACT == 1) {
; #pragma unroll
;                         for (int e = 0; e < 4; ++e) { float a = v0[e] > 0.f ? v0[e] : 0.f; v0[e] = a * a; float b = v1[e] > 0.f ? v1[e] : 0.f; v1[e] = b * b; } }
;                     u32x4 w; w.x = cvt_pk_bf16(v0[0], v0[1]); w.y = cvt_pk_bf16(v0[2], v0[3]); w.z = cvt_pk_bf16(v1[0], v1[1]); w.w = cvt_pk_bf16(v1[2], v1[3]);
;                     *(PG8_GAS u32x4*)(rowp + bj * HALF) = w; } }
.LBB0_642:
	s_and_b64 vcc, exec, s[0:1]
	s_mov_b64 s[0:1], -1
	v_cvt_pk_bf16_f32 v4, v4, v5
	v_cvt_pk_bf16_f32 v5, v6, v7
	v_cvt_pk_bf16_f32 v6, v0, v1
	v_cvt_pk_bf16_f32 v7, v2, v3
	global_store_dwordx4 v[8:9], v[4:7], off offset:256 sc0 sc1
	s_cbranch_vccnz .LBB0_448
	s_andn2_b64 vcc, exec, s[92:93]
	s_cbranch_vccnz .LBB0_447
	s_barrier
	s_branch .LBB0_447
